# P5 epilogue stores lane-transposed for 64B-contiguous quads; P3 epilogue loads hoisted into a register ring with counted vmcnt
# speedup vs baseline: 1.0032x; 1.0025x over previous
; __device__ __forceinline__ float bf_lo(unsigned w) { return __uint_as_float(w << 16); }
; __device__ __forceinline__ float bf_hi(unsigned w) { return __uint_as_float(w & 0xffff0000u); }
; __device__ __forceinline__ u32x4 pack8(const f32x4 a, const f32x4 b) { u32x4 w; w.x = cvt_pk_bf16(a[0], a[1]); w.y = cvt_pk_bf16(a[2], a[3]); w.z = cvt_pk_bf16(b[0], b[1]); w.w = cvt_pk_bf16(b[2], b[3]); return w; }
;     __device__ __forceinline__ void operator()(const f32x4 (&acc)[2][2][4][2], const Unit& u, int wr, int wc, int fr, int fq) const {
;         const int row0 = u.pm * BM + wr * 64 + fr, col0 = u.pn * BM + wc * 32 + 8 * fq;
;         f32x4 ps[2][2];
; #pragma unroll
;         for (int bj = 0; bj < 2; ++bj) { ps[bj][0] = *(const f32x4*)(pscale + col0 + bj * HALF); ps[bj][1] = *(const f32x4*)(pscale + col0 + bj * HALF + 4); }
; #pragma unroll
;         for (int ai = 0; ai < 2; ++ai)
; #pragma unroll
;             for (int m = 0; m < 4; ++m) {
;                 const size_t row = (size_t)(row0 + ai * HALF + m * 16);
; #pragma unroll
;                 for (int bj = 0; bj < 2; ++bj) {
;                     const int c = col0 + bj * HALF;
;                     const u32x4 a8 = __builtin_nontemporal_load((const u32x4*)(A + row * 1024 + c)), ga = __builtin_nontemporal_load((const u32x4*)(G + row * 2048 + c)), gp = __builtin_nontemporal_load((const u32x4*)(G + row * 2048 + 1024 + c));
;                     const f32x4 y0 = acc[ai][bj][m][0] * ps[bj][0], y1 = acc[ai][bj][m][1] * ps[bj][1];
;                     f32x4 o0, o1;
;                     o0[0] = bf_lo(ga.x) * bf_lo(a8.x) + bf_lo(gp.x) * y0[0]; o0[1] = bf_hi(ga.x) * bf_hi(a8.x) + bf_hi(gp.x) * y0[1];
;                     o0[2] = bf_lo(ga.y) * bf_lo(a8.y) + bf_lo(gp.y) * y0[2]; o0[3] = bf_hi(ga.y) * bf_hi(a8.y) + bf_hi(gp.y) * y0[3];
;                     o1[0] = bf_lo(ga.z) * bf_lo(a8.z) + bf_lo(gp.z) * y1[0]; o1[1] = bf_hi(ga.z) * bf_hi(a8.z) + bf_hi(gp.z) * y1[1];
;                     o1[2] = bf_lo(ga.w) * bf_lo(a8.w) + bf_lo(gp.w) * y1[2]; o1[3] = bf_hi(ga.w) * bf_hi(a8.w) + bf_hi(gp.w) * y1[3];
;                     __builtin_nontemporal_store(pack8(o0, o1), (u32x4*)(Mg + row * 1024 + c));
.LBB0_381:
	v_lshl_add_u32 v158, s22, 8, v160
	v_lshl_or_b32 v8, s39, 8, v162
	v_ashrrev_i32_e32 v159, 31, v158
	v_ashrrev_i32_e32 v9, 31, v8
	v_lshlrev_b32_e32 v246, 11, v158
	v_lshl_add_u32 v246, v8, 1, v246
	v_lshlrev_b32_e32 v247, 12, v158
	v_lshl_add_u32 v247, v8, 1, v247
	global_load_dwordx4 v[210:213], v246, s[46:47] nt
	global_load_dwordx4 v[214:217], v247, s[62:63] offset:2048 nt
	global_load_dwordx4 v[218:221], v247, s[62:63] nt
	global_load_dwordx4 v[222:225], v246, s[46:47] offset:256 nt
	global_load_dwordx4 v[226:229], v247, s[62:63] offset:2304 nt
	global_load_dwordx4 v[230:233], v247, s[62:63] offset:256 nt
	v_add_u32_e32 v248, 0x8000, v246
	global_load_dwordx4 v[234:237], v248, s[46:47] nt
	v_add_u32_e32 v248, 0x10000, v247
	global_load_dwordx4 v[238:241], v248, s[62:63] offset:2048 nt
	global_load_dwordx4 v[242:245], v248, s[62:63] nt
	v_lshlrev_b64 v[152:153], 11, v[158:159]
	v_lshl_add_u64 v[12:13], v[8:9], 2, s[44:45]
	v_lshl_add_u64 v[14:15], s[46:47], 0, v[152:153]
	v_lshlrev_b64 v[156:157], 1, v[8:9]
	global_load_dwordx4 v[24:27], v[12:13], off offset:16
	global_load_dwordx4 v[28:31], v[12:13], off
	v_lshlrev_b64 v[10:11], 12, v[158:159]
	v_lshl_add_u64 v[178:179], v[14:15], 0, v[156:157]
	v_lshl_add_u64 v[8:9], s[62:63], 0, v[10:11]
	v_lshl_add_u64 v[180:181], v[8:9], 0, v[156:157]
	global_load_dwordx4 v[8:11], v[12:13], off offset:528
	s_nop 0
	global_load_dwordx4 v[12:15], v[12:13], off offset:512
	s_andn2_b64 vcc, exec, s[2:3]
	s_mov_b64 s[2:3], -1
	s_waitcnt vmcnt(3)
	v_pk_mul_f32 v[138:139], v[138:139], v[26:27]
	s_waitcnt vmcnt(2)
	v_pk_mul_f32 v[142:143], v[142:143], v[30:31]
	v_pk_mul_f32 v[140:141], v[140:141], v[28:29]
	v_pk_mul_f32 v[136:137], v[136:137], v[24:25]
	v_mov_b32_e32 v183, v140
	v_mov_b32_e32 v185, v142
	v_mov_b32_e32 v187, v136
	v_mov_b32_e32 v189, v138
	v_lshlrev_b32_e32 v182, 16, v210
	v_lshlrev_b32_e32 v193, 16, v214
	v_and_b32_e32 v140, 0xffff0000, v210
	v_and_b32_e32 v195, 0xffff0000, v214
	v_and_b32_e32 v194, 0xffff0000, v218
	v_lshlrev_b32_e32 v184, 16, v211
	v_lshlrev_b32_e32 v197, 16, v215
	v_lshlrev_b32_e32 v196, 16, v219
	v_and_b32_e32 v142, 0xffff0000, v211
	v_and_b32_e32 v167, 0xffff0000, v215
	v_and_b32_e32 v166, 0xffff0000, v219
	v_lshlrev_b32_e32 v186, 16, v212
	v_lshlrev_b32_e32 v171, 16, v216
	v_lshlrev_b32_e32 v170, 16, v220
	v_and_b32_e32 v136, 0xffff0000, v212
	v_lshlrev_b32_e32 v188, 16, v213
	v_and_b32_e32 v138, 0xffff0000, v213
	v_add_u32_e32 v248, 0x8000, v246
	global_load_dwordx4 v[210:213], v248, s[46:47] offset:256 nt
	v_and_b32_e32 v169, 0xffff0000, v217
	v_and_b32_e32 v168, 0xffff0000, v221
	v_lshlrev_b32_e32 v192, 16, v218
	v_and_b32_e32 v175, 0xffff0000, v216
	v_and_b32_e32 v174, 0xffff0000, v220
	v_lshlrev_b32_e32 v199, 16, v217
	v_add_u32_e32 v248, 0x10000, v247
	global_load_dwordx4 v[214:217], v248, s[62:63] offset:2304 nt
	v_lshlrev_b32_e32 v198, 16, v221
	global_load_dwordx4 v[218:221], v248, s[62:63] offset:256 nt
	v_pk_mul_f32 v[140:141], v[140:141], v[194:195]
	v_pk_mul_f32 v[176:177], v[184:185], v[196:197]
	v_pk_mul_f32 v[142:143], v[142:143], v[166:167]
	v_pk_mul_f32 v[166:167], v[186:187], v[170:171]
	v_pk_mul_f32 v[138:139], v[138:139], v[168:169]
	v_pk_mul_f32 v[172:173], v[182:183], v[192:193]
	v_pk_mul_f32 v[136:137], v[136:137], v[174:175]
	v_pk_mul_f32 v[170:171], v[188:189], v[198:199]
	v_add_f32_e32 v140, v140, v141
	v_add_f32_e32 v141, v176, v177
	v_add_f32_e32 v142, v142, v143
	v_add_f32_e32 v143, v166, v167
	v_add_f32_e32 v166, v138, v139
	v_add_f32_e32 v159, v172, v173
	v_add_f32_e32 v136, v136, v137
	v_add_f32_e32 v137, v170, v171
	v_cvt_pk_bf16_f32 v138, v159, v140
	v_cvt_pk_bf16_f32 v139, v141, v142
	v_cvt_pk_bf16_f32 v140, v143, v136
	v_cvt_pk_bf16_f32 v141, v137, v166
	v_lshl_add_u64 v[142:143], s[60:61], 0, v[152:153]
	v_lshl_add_u64 v[142:143], v[142:143], 0, v[156:157]
	s_waitcnt vmcnt(3)
	v_pk_mul_f32 v[130:131], v[130:131], v[14:15]
	v_pk_mul_f32 v[128:129], v[128:129], v[12:13]
	v_pk_mul_f32 v[132:133], v[132:133], v[8:9]
	v_or_b32_e32 v136, 16, v158
	v_pk_mul_f32 v[134:135], v[134:135], v[10:11]
	v_mov_b32_e32 v181, v128
	v_mov_b32_e32 v183, v130
	v_mov_b32_e32 v185, v132
	global_store_dwordx4 v[142:143], v[138:141], off nt
	v_ashrrev_i32_e32 v137, 31, v136
	v_mov_b32_e32 v187, v134
	v_lshlrev_b64 v[152:153], 12, v[136:137]
	v_lshlrev_b64 v[136:137], 11, v[136:137]
	v_lshl_add_u64 v[178:179], s[46:47], 0, v[136:137]
	v_lshl_add_u64 v[152:153], s[62:63], 0, v[152:153]
	v_lshl_add_u64 v[178:179], v[178:179], 0, v[156:157]
	v_lshl_add_u64 v[152:153], v[152:153], 0, v[156:157]
	v_pk_mul_f32 v[126:127], v[126:127], v[30:31]
	v_pk_mul_f32 v[124:125], v[124:125], v[28:29]
	v_pk_mul_f32 v[122:123], v[122:123], v[26:27]
	v_pk_mul_f32 v[120:121], v[120:121], v[24:25]
	v_lshl_add_u64 v[136:137], s[60:61], 0, v[136:137]
	v_lshl_add_u64 v[136:137], v[136:137], 0, v[156:157]
	v_pk_mul_f32 v[114:115], v[114:115], v[14:15]
	v_pk_mul_f32 v[112:113], v[112:113], v[12:13]
	v_pk_mul_f32 v[116:117], v[116:117], v[8:9]
	v_pk_mul_f32 v[118:119], v[118:119], v[10:11]
	v_pk_mul_f32 v[110:111], v[110:111], v[30:31]
	v_pk_mul_f32 v[108:109], v[108:109], v[28:29]
	v_pk_mul_f32 v[106:107], v[106:107], v[26:27]
	v_pk_mul_f32 v[104:105], v[104:105], v[24:25]
	v_pk_mul_f32 v[98:99], v[98:99], v[14:15]
	v_pk_mul_f32 v[96:97], v[96:97], v[12:13]
	v_pk_mul_f32 v[100:101], v[100:101], v[8:9]
	v_pk_mul_f32 v[102:103], v[102:103], v[10:11]
	v_pk_mul_f32 v[94:95], v[94:95], v[30:31]
	v_pk_mul_f32 v[92:93], v[92:93], v[28:29]
	v_pk_mul_f32 v[90:91], v[90:91], v[26:27]
	v_pk_mul_f32 v[88:89], v[88:89], v[24:25]
	v_pk_mul_f32 v[82:83], v[82:83], v[14:15]
; __device__ __forceinline__ float bf_lo(unsigned w) { return __uint_as_float(w << 16); }
; __device__ __forceinline__ float bf_hi(unsigned w) { return __uint_as_float(w & 0xffff0000u); }
; __device__ __forceinline__ u32x4 pack8(const f32x4 a, const f32x4 b) { u32x4 w; w.x = cvt_pk_bf16(a[0], a[1]); w.y = cvt_pk_bf16(a[2], a[3]); w.z = cvt_pk_bf16(b[0], b[1]); w.w = cvt_pk_bf16(b[2], b[3]); return w; }
;     __device__ __forceinline__ void operator()(const f32x4 (&acc)[2][2][4][2], const Unit& u, int wr, int wc, int fr, int fq) const {
;     ...
;         for (int ai = 0; ai < 2; ++ai)
; #pragma unroll
;             for (int m = 0; m < 4; ++m) {
;                 const size_t row = (size_t)(row0 + ai * HALF + m * 16);
; #pragma unroll
;                 for (int bj = 0; bj < 2; ++bj) {
;                     const int c = col0 + bj * HALF;
;                     const u32x4 a8 = __builtin_nontemporal_load((const u32x4*)(A + row * 1024 + c)), ga = __builtin_nontemporal_load((const u32x4*)(G + row * 2048 + c)), gp = __builtin_nontemporal_load((const u32x4*)(G + row * 2048 + 1024 + c));
;                     const f32x4 y0 = acc[ai][bj][m][0] * ps[bj][0], y1 = acc[ai][bj][m][1] * ps[bj][1];
;                     f32x4 o0, o1;
;                     o0[0] = bf_lo(ga.x) * bf_lo(a8.x) + bf_lo(gp.x) * y0[0]; o0[1] = bf_hi(ga.x) * bf_hi(a8.x) + bf_hi(gp.x) * y0[1];
;                     o0[2] = bf_lo(ga.y) * bf_lo(a8.y) + bf_lo(gp.y) * y0[2]; o0[3] = bf_hi(ga.y) * bf_hi(a8.y) + bf_hi(gp.y) * y0[3];
;                     o1[0] = bf_lo(ga.z) * bf_lo(a8.z) + bf_lo(gp.z) * y1[0]; o1[1] = bf_hi(ga.z) * bf_hi(a8.z) + bf_hi(gp.z) * y1[1];
;                     o1[2] = bf_lo(ga.w) * bf_lo(a8.w) + bf_lo(gp.w) * y1[2]; o1[3] = bf_hi(ga.w) * bf_hi(a8.w) + bf_hi(gp.w) * y1[3];
;                     __builtin_nontemporal_store(pack8(o0, o1), (u32x4*)(Mg + row * 1024 + c));
;                 }
	v_pk_mul_f32 v[80:81], v[80:81], v[12:13]
	v_pk_mul_f32 v[84:85], v[84:85], v[8:9]
	v_pk_mul_f32 v[86:87], v[86:87], v[10:11]
	v_pk_mul_f32 v[78:79], v[78:79], v[30:31]
	v_pk_mul_f32 v[76:77], v[76:77], v[28:29]
	v_pk_mul_f32 v[74:75], v[74:75], v[26:27]
	v_pk_mul_f32 v[72:73], v[72:73], v[24:25]
	v_pk_mul_f32 v[66:67], v[66:67], v[14:15]
	v_pk_mul_f32 v[64:65], v[64:65], v[12:13]
	v_pk_mul_f32 v[68:69], v[68:69], v[8:9]
	v_pk_mul_f32 v[70:71], v[70:71], v[10:11]
	v_pk_mul_f32 v[62:63], v[62:63], v[30:31]
	v_pk_mul_f32 v[60:61], v[60:61], v[28:29]
	v_pk_mul_f32 v[58:59], v[58:59], v[26:27]
	v_pk_mul_f32 v[56:57], v[56:57], v[24:25]
	v_pk_mul_f32 v[50:51], v[50:51], v[14:15]
	v_pk_mul_f32 v[48:49], v[48:49], v[12:13]
	v_pk_mul_f32 v[52:53], v[52:53], v[8:9]
	v_pk_mul_f32 v[54:55], v[54:55], v[10:11]
	v_pk_mul_f32 v[46:47], v[46:47], v[30:31]
	v_pk_mul_f32 v[44:45], v[44:45], v[28:29]
	v_pk_mul_f32 v[42:43], v[42:43], v[26:27]
	v_pk_mul_f32 v[40:41], v[40:41], v[24:25]
	v_pk_mul_f32 v[34:35], v[34:35], v[14:15]
	v_pk_mul_f32 v[32:33], v[32:33], v[12:13]
	v_pk_mul_f32 v[36:37], v[36:37], v[8:9]
	v_pk_mul_f32 v[38:39], v[38:39], v[10:11]
	v_pk_mul_f32 v[22:23], v[22:23], v[30:31]
	v_pk_mul_f32 v[20:21], v[20:21], v[28:29]
	v_pk_mul_f32 v[18:19], v[18:19], v[26:27]
	v_pk_mul_f32 v[16:17], v[16:17], v[24:25]
	v_mov_b32_e32 v25, v20
	v_mov_b32_e32 v27, v22
	v_mov_b32_e32 v29, v16
	v_mov_b32_e32 v31, v18
	v_lshlrev_b32_e32 v180, 16, v222
	v_lshlrev_b32_e32 v139, 16, v226
	v_and_b32_e32 v128, 0xffff0000, v222
	v_and_b32_e32 v141, 0xffff0000, v226
	v_and_b32_e32 v140, 0xffff0000, v230
	v_lshlrev_b32_e32 v182, 16, v223
	v_lshlrev_b32_e32 v189, 16, v227
	v_lshlrev_b32_e32 v188, 16, v231
	v_and_b32_e32 v130, 0xffff0000, v223
	v_and_b32_e32 v167, 0xffff0000, v227
	v_and_b32_e32 v166, 0xffff0000, v231
	v_lshlrev_b32_e32 v184, 16, v224
	v_lshlrev_b32_e32 v171, 16, v228
	v_lshlrev_b32_e32 v170, 16, v232
	v_lshlrev_b32_e32 v138, 16, v230
	v_and_b32_e32 v132, 0xffff0000, v224
	v_and_b32_e32 v175, 0xffff0000, v228
	v_and_b32_e32 v174, 0xffff0000, v232
	v_lshlrev_b32_e32 v186, 16, v225
	v_lshlrev_b32_e32 v193, 16, v229
	v_lshlrev_b32_e32 v192, 16, v233
	v_and_b32_e32 v134, 0xffff0000, v225
	v_add_u32_e32 v248, 0x10000, v246
	global_load_dwordx4 v[222:225], v248, s[46:47] nt
	v_and_b32_e32 v169, 0xffff0000, v229
	v_add_u32_e32 v248, 0x20000, v247
	global_load_dwordx4 v[226:229], v248, s[62:63] offset:2048 nt
	v_and_b32_e32 v168, 0xffff0000, v233
	global_load_dwordx4 v[230:233], v248, s[62:63] nt
	v_pk_mul_f32 v[128:129], v[128:129], v[140:141]
	v_pk_mul_f32 v[140:141], v[182:183], v[188:189]
	v_pk_mul_f32 v[130:131], v[130:131], v[166:167]
	v_pk_mul_f32 v[166:167], v[184:185], v[170:171]
	v_pk_mul_f32 v[138:139], v[180:181], v[138:139]
	v_pk_mul_f32 v[132:133], v[132:133], v[174:175]
	v_pk_mul_f32 v[170:171], v[186:187], v[192:193]
	v_pk_mul_f32 v[134:135], v[134:135], v[168:169]
	v_add_f32_e32 v128, v128, v129
	v_add_f32_e32 v129, v140, v141
	v_add_f32_e32 v130, v130, v131
	v_add_f32_e32 v131, v166, v167
	v_add_f32_e32 v138, v138, v139
	v_add_f32_e32 v132, v132, v133
	v_add_f32_e32 v133, v170, v171
	v_add_f32_e32 v134, v134, v135
	v_cvt_pk_bf16_f32 v128, v138, v128
	v_cvt_pk_bf16_f32 v129, v129, v130
	v_cvt_pk_bf16_f32 v130, v131, v132
	v_cvt_pk_bf16_f32 v131, v133, v134
	global_store_dwordx4 v[142:143], v[128:131], off offset:256 nt
	v_mov_b32_e32 v143, v124
	v_mov_b32_e32 v167, v126
	v_mov_b32_e32 v169, v120
	v_mov_b32_e32 v171, v122
	v_pk_mul_f32 v[2:3], v[2:3], v[10:11]
	v_pk_mul_f32 v[0:1], v[0:1], v[8:9]
	v_pk_mul_f32 v[6:7], v[6:7], v[14:15]
	v_pk_mul_f32 v[4:5], v[4:5], v[12:13]
	v_mov_b32_e32 v13, v0
	v_mov_b32_e32 v15, v2
	v_mov_b32_e32 v9, v4
	v_mov_b32_e32 v11, v6
	v_lshlrev_b32_e32 v142, 16, v234
	v_lshlrev_b32_e32 v173, 16, v238
	v_lshlrev_b32_e32 v172, 16, v242
	v_and_b32_e32 v124, 0xffff0000, v234
	v_and_b32_e32 v175, 0xffff0000, v238
	v_and_b32_e32 v174, 0xffff0000, v242
	v_lshlrev_b32_e32 v166, 16, v235
	v_lshlrev_b32_e32 v177, 16, v239
	v_lshlrev_b32_e32 v176, 16, v243
	v_and_b32_e32 v126, 0xffff0000, v235
	v_and_b32_e32 v129, 0xffff0000, v239
	v_and_b32_e32 v128, 0xffff0000, v243
	v_lshlrev_b32_e32 v168, 16, v236
	v_lshlrev_b32_e32 v133, 16, v240
	v_lshlrev_b32_e32 v132, 16, v244
	v_and_b32_e32 v120, 0xffff0000, v236
	v_lshlrev_b32_e32 v170, 16, v237
	v_and_b32_e32 v122, 0xffff0000, v237
	v_add_u32_e32 v248, 0x10000, v246
	global_load_dwordx4 v[234:237], v248, s[46:47] offset:256 nt
	v_and_b32_e32 v131, 0xffff0000, v241
	v_and_b32_e32 v130, 0xffff0000, v245
	v_and_b32_e32 v139, 0xffff0000, v240
	v_and_b32_e32 v138, 0xffff0000, v244
	v_lshlrev_b32_e32 v181, 16, v241
	v_add_u32_e32 v248, 0x20000, v247
	global_load_dwordx4 v[238:241], v248, s[62:63] offset:2304 nt
	v_lshlrev_b32_e32 v180, 16, v245
	global_load_dwordx4 v[242:245], v248, s[62:63] offset:256 nt
	v_pk_mul_f32 v[134:135], v[142:143], v[172:173]
	v_pk_mul_f32 v[124:125], v[124:125], v[174:175]
	v_pk_mul_f32 v[140:141], v[166:167], v[176:177]
	v_pk_mul_f32 v[126:127], v[126:127], v[128:129]
	v_pk_mul_f32 v[128:129], v[168:169], v[132:133]
	v_pk_mul_f32 v[122:123], v[122:123], v[130:131]
	v_pk_mul_f32 v[120:121], v[120:121], v[138:139]
	v_pk_mul_f32 v[132:133], v[170:171], v[180:181]
	v_add_f32_e32 v130, v134, v135
	v_add_f32_e32 v124, v124, v125
	v_add_f32_e32 v125, v140, v141
	v_add_f32_e32 v126, v126, v127
	v_add_f32_e32 v127, v128, v129
	v_add_f32_e32 v128, v122, v123
	v_add_f32_e32 v120, v120, v121
	v_add_f32_e32 v121, v132, v133
	v_cvt_pk_bf16_f32 v122, v130, v124
	v_cvt_pk_bf16_f32 v123, v125, v126
	v_cvt_pk_bf16_f32 v124, v127, v120
	v_cvt_pk_bf16_f32 v125, v121, v128
	v_or_b32_e32 v120, 32, v158
	v_mov_b32_e32 v153, v112
	v_mov_b32_e32 v167, v114
	v_mov_b32_e32 v169, v116
	global_store_dwordx4 v[136:137], v[122:125], off nt
	v_ashrrev_i32_e32 v121, 31, v120
	v_mov_b32_e32 v171, v118
	v_lshlrev_b64 v[134:135], 12, v[120:121]
	v_lshlrev_b64 v[120:121], 11, v[120:121]
	v_lshl_add_u64 v[142:143], s[46:47], 0, v[120:121]
	v_lshl_add_u64 v[134:135], s[62:63], 0, v[134:135]
	v_lshl_add_u64 v[142:143], v[142:143], 0, v[156:157]
	v_lshl_add_u64 v[134:135], v[134:135], 0, v[156:157]
	v_lshl_add_u64 v[120:121], s[60:61], 0, v[120:121]
	v_lshl_add_u64 v[120:121], v[120:121], 0, v[156:157]
	s_waitcnt vmcnt(11)
; __device__ __forceinline__ float bf_lo(unsigned w) { return __uint_as_float(w << 16); }
; __device__ __forceinline__ float bf_hi(unsigned w) { return __uint_as_float(w & 0xffff0000u); }
; __device__ __forceinline__ u32x4 pack8(const f32x4 a, const f32x4 b) { u32x4 w; w.x = cvt_pk_bf16(a[0], a[1]); w.y = cvt_pk_bf16(a[2], a[3]); w.z = cvt_pk_bf16(b[0], b[1]); w.w = cvt_pk_bf16(b[2], b[3]); return w; }
;     __device__ __forceinline__ void operator()(const f32x4 (&acc)[2][2][4][2], const Unit& u, int wr, int wc, int fr, int fq) const {
;     ...
;         for (int ai = 0; ai < 2; ++ai)
; #pragma unroll
;             for (int m = 0; m < 4; ++m) {
;                 const size_t row = (size_t)(row0 + ai * HALF + m * 16);
; #pragma unroll
;                 for (int bj = 0; bj < 2; ++bj) {
;                     const int c = col0 + bj * HALF;
;                     const u32x4 a8 = __builtin_nontemporal_load((const u32x4*)(A + row * 1024 + c)), ga = __builtin_nontemporal_load((const u32x4*)(G + row * 2048 + c)), gp = __builtin_nontemporal_load((const u32x4*)(G + row * 2048 + 1024 + c));
;                     const f32x4 y0 = acc[ai][bj][m][0] * ps[bj][0], y1 = acc[ai][bj][m][1] * ps[bj][1];
;                     f32x4 o0, o1;
;                     o0[0] = bf_lo(ga.x) * bf_lo(a8.x) + bf_lo(gp.x) * y0[0]; o0[1] = bf_hi(ga.x) * bf_hi(a8.x) + bf_hi(gp.x) * y0[1];
;                     o0[2] = bf_lo(ga.y) * bf_lo(a8.y) + bf_lo(gp.y) * y0[2]; o0[3] = bf_hi(ga.y) * bf_hi(a8.y) + bf_hi(gp.y) * y0[3];
;                     o1[0] = bf_lo(ga.z) * bf_lo(a8.z) + bf_lo(gp.z) * y1[0]; o1[1] = bf_hi(ga.z) * bf_hi(a8.z) + bf_hi(gp.z) * y1[1];
;                     o1[2] = bf_lo(ga.w) * bf_lo(a8.w) + bf_lo(gp.w) * y1[2]; o1[3] = bf_hi(ga.w) * bf_hi(a8.w) + bf_hi(gp.w) * y1[3];
;                     __builtin_nontemporal_store(pack8(o0, o1), (u32x4*)(Mg + row * 1024 + c));
;                 }
	v_lshlrev_b32_e32 v152, 16, v210
	s_waitcnt vmcnt(10)
	v_lshlrev_b32_e32 v123, 16, v214
	v_and_b32_e32 v112, 0xffff0000, v210
	v_and_b32_e32 v125, 0xffff0000, v214
	s_waitcnt vmcnt(9)
	v_and_b32_e32 v124, 0xffff0000, v218
	v_lshlrev_b32_e32 v166, 16, v211
	v_lshlrev_b32_e32 v173, 16, v215
	v_lshlrev_b32_e32 v172, 16, v219
	v_and_b32_e32 v114, 0xffff0000, v211
	v_and_b32_e32 v127, 0xffff0000, v215
	v_and_b32_e32 v126, 0xffff0000, v219
	v_lshlrev_b32_e32 v168, 16, v212
	v_lshlrev_b32_e32 v131, 16, v216
	v_lshlrev_b32_e32 v130, 16, v220
	v_lshlrev_b32_e32 v122, 16, v218
	v_and_b32_e32 v116, 0xffff0000, v212
	v_and_b32_e32 v139, 0xffff0000, v216
	v_and_b32_e32 v138, 0xffff0000, v220
	v_lshlrev_b32_e32 v170, 16, v213
	v_lshlrev_b32_e32 v175, 16, v217
	v_lshlrev_b32_e32 v174, 16, v221
	v_and_b32_e32 v118, 0xffff0000, v213
	v_add_u32_e32 v248, 0x18000, v246
	global_load_dwordx4 v[210:213], v248, s[46:47] nt
	v_and_b32_e32 v129, 0xffff0000, v217
	v_add_u32_e32 v248, 0x30000, v247
	global_load_dwordx4 v[214:217], v248, s[62:63] offset:2048 nt
	v_and_b32_e32 v128, 0xffff0000, v221
	global_load_dwordx4 v[218:221], v248, s[62:63] nt
	v_pk_mul_f32 v[112:113], v[112:113], v[124:125]
	v_pk_mul_f32 v[124:125], v[166:167], v[172:173]
	v_pk_mul_f32 v[114:115], v[114:115], v[126:127]
	v_pk_mul_f32 v[126:127], v[168:169], v[130:131]
	v_pk_mul_f32 v[122:123], v[152:153], v[122:123]
	v_pk_mul_f32 v[116:117], v[116:117], v[138:139]
	v_pk_mul_f32 v[130:131], v[170:171], v[174:175]
	v_pk_mul_f32 v[118:119], v[118:119], v[128:129]
	v_add_f32_e32 v112, v112, v113
	v_add_f32_e32 v113, v124, v125
	v_add_f32_e32 v114, v114, v115
	v_add_f32_e32 v115, v126, v127
	v_add_f32_e32 v122, v122, v123
	v_add_f32_e32 v116, v116, v117
	v_add_f32_e32 v117, v130, v131
	v_add_f32_e32 v118, v118, v119
	v_cvt_pk_bf16_f32 v112, v122, v112
	v_cvt_pk_bf16_f32 v113, v113, v114
	v_cvt_pk_bf16_f32 v114, v115, v116
	v_cvt_pk_bf16_f32 v115, v117, v118
	global_store_dwordx4 v[136:137], v[112:115], off offset:256 nt
	v_mov_b32_e32 v127, v108
	v_mov_b32_e32 v129, v110
	v_mov_b32_e32 v131, v104
	v_mov_b32_e32 v133, v106
	s_waitcnt vmcnt(11)
	v_lshlrev_b32_e32 v126, 16, v222
	s_waitcnt vmcnt(10)
	v_lshlrev_b32_e32 v137, 16, v226
	s_waitcnt vmcnt(9)
	v_lshlrev_b32_e32 v136, 16, v230
	v_and_b32_e32 v108, 0xffff0000, v222
	v_and_b32_e32 v139, 0xffff0000, v226
	v_and_b32_e32 v138, 0xffff0000, v230
	v_lshlrev_b32_e32 v128, 16, v223
	v_lshlrev_b32_e32 v141, 16, v227
	v_lshlrev_b32_e32 v140, 16, v231
	v_and_b32_e32 v110, 0xffff0000, v223
	v_and_b32_e32 v113, 0xffff0000, v227
	v_and_b32_e32 v112, 0xffff0000, v231
	v_lshlrev_b32_e32 v130, 16, v224
	v_lshlrev_b32_e32 v117, 16, v228
	v_lshlrev_b32_e32 v116, 16, v232
	v_and_b32_e32 v104, 0xffff0000, v224
	v_lshlrev_b32_e32 v132, 16, v225
	v_and_b32_e32 v106, 0xffff0000, v225
	v_add_u32_e32 v248, 0x18000, v246
	global_load_dwordx4 v[222:225], v248, s[46:47] offset:256 nt
	v_and_b32_e32 v115, 0xffff0000, v229
	v_and_b32_e32 v114, 0xffff0000, v233
	v_and_b32_e32 v123, 0xffff0000, v228
	v_and_b32_e32 v122, 0xffff0000, v232
	v_lshlrev_b32_e32 v153, 16, v229
	v_add_u32_e32 v248, 0x30000, v247
	global_load_dwordx4 v[226:229], v248, s[62:63] offset:2304 nt
	v_lshlrev_b32_e32 v152, 16, v233
	global_load_dwordx4 v[230:233], v248, s[62:63] offset:256 nt
	v_pk_mul_f32 v[118:119], v[126:127], v[136:137]
	v_pk_mul_f32 v[108:109], v[108:109], v[138:139]
	v_pk_mul_f32 v[124:125], v[128:129], v[140:141]
	v_pk_mul_f32 v[110:111], v[110:111], v[112:113]
	v_pk_mul_f32 v[112:113], v[130:131], v[116:117]
	v_pk_mul_f32 v[106:107], v[106:107], v[114:115]
	v_pk_mul_f32 v[104:105], v[104:105], v[122:123]
	v_pk_mul_f32 v[116:117], v[132:133], v[152:153]
	v_add_f32_e32 v114, v118, v119
	v_add_f32_e32 v108, v108, v109
	v_add_f32_e32 v109, v124, v125
	v_add_f32_e32 v110, v110, v111
	v_add_f32_e32 v111, v112, v113
	v_add_f32_e32 v112, v106, v107
	v_add_f32_e32 v104, v104, v105
	v_add_f32_e32 v105, v116, v117
	v_cvt_pk_bf16_f32 v106, v114, v108
	v_cvt_pk_bf16_f32 v107, v109, v110
	v_cvt_pk_bf16_f32 v108, v111, v104
	v_cvt_pk_bf16_f32 v109, v105, v112
	v_or_b32_e32 v104, 48, v158
	v_mov_b32_e32 v129, v96
	v_mov_b32_e32 v131, v98
	v_mov_b32_e32 v133, v100
	global_store_dwordx4 v[120:121], v[106:109], off nt
	v_ashrrev_i32_e32 v105, 31, v104
	v_mov_b32_e32 v135, v102
	v_lshlrev_b64 v[118:119], 12, v[104:105]
	v_lshlrev_b64 v[104:105], 11, v[104:105]
	v_lshl_add_u64 v[126:127], s[46:47], 0, v[104:105]
	v_lshl_add_u64 v[118:119], s[62:63], 0, v[118:119]
	v_lshl_add_u64 v[126:127], v[126:127], 0, v[156:157]
	v_lshl_add_u64 v[118:119], v[118:119], 0, v[156:157]
	v_lshl_add_u64 v[104:105], s[60:61], 0, v[104:105]
	v_lshl_add_u64 v[104:105], v[104:105], 0, v[156:157]
	s_waitcnt vmcnt(11)
	v_lshlrev_b32_e32 v128, 16, v234
	s_waitcnt vmcnt(10)
	v_lshlrev_b32_e32 v107, 16, v238
	v_and_b32_e32 v96, 0xffff0000, v234
	v_and_b32_e32 v109, 0xffff0000, v238
	s_waitcnt vmcnt(9)
; __device__ __forceinline__ float bf_lo(unsigned w) { return __uint_as_float(w << 16); }
; __device__ __forceinline__ float bf_hi(unsigned w) { return __uint_as_float(w & 0xffff0000u); }
; __device__ __forceinline__ u32x4 pack8(const f32x4 a, const f32x4 b) { u32x4 w; w.x = cvt_pk_bf16(a[0], a[1]); w.y = cvt_pk_bf16(a[2], a[3]); w.z = cvt_pk_bf16(b[0], b[1]); w.w = cvt_pk_bf16(b[2], b[3]); return w; }
;     __device__ __forceinline__ void operator()(const f32x4 (&acc)[2][2][4][2], const Unit& u, int wr, int wc, int fr, int fq) const {
;     ...
;         for (int ai = 0; ai < 2; ++ai)
; #pragma unroll
;             for (int m = 0; m < 4; ++m) {
;                 const size_t row = (size_t)(row0 + ai * HALF + m * 16);
; #pragma unroll
;                 for (int bj = 0; bj < 2; ++bj) {
;                     const int c = col0 + bj * HALF;
;                     const u32x4 a8 = __builtin_nontemporal_load((const u32x4*)(A + row * 1024 + c)), ga = __builtin_nontemporal_load((const u32x4*)(G + row * 2048 + c)), gp = __builtin_nontemporal_load((const u32x4*)(G + row * 2048 + 1024 + c));
;                     const f32x4 y0 = acc[ai][bj][m][0] * ps[bj][0], y1 = acc[ai][bj][m][1] * ps[bj][1];
;                     f32x4 o0, o1;
;                     o0[0] = bf_lo(ga.x) * bf_lo(a8.x) + bf_lo(gp.x) * y0[0]; o0[1] = bf_hi(ga.x) * bf_hi(a8.x) + bf_hi(gp.x) * y0[1];
;                     o0[2] = bf_lo(ga.y) * bf_lo(a8.y) + bf_lo(gp.y) * y0[2]; o0[3] = bf_hi(ga.y) * bf_hi(a8.y) + bf_hi(gp.y) * y0[3];
;                     o1[0] = bf_lo(ga.z) * bf_lo(a8.z) + bf_lo(gp.z) * y1[0]; o1[1] = bf_hi(ga.z) * bf_hi(a8.z) + bf_hi(gp.z) * y1[1];
;                     o1[2] = bf_lo(ga.w) * bf_lo(a8.w) + bf_lo(gp.w) * y1[2]; o1[3] = bf_hi(ga.w) * bf_hi(a8.w) + bf_hi(gp.w) * y1[3];
;                     __builtin_nontemporal_store(pack8(o0, o1), (u32x4*)(Mg + row * 1024 + c));
;                 }
	v_and_b32_e32 v108, 0xffff0000, v242
	v_lshlrev_b32_e32 v130, 16, v235
	v_lshlrev_b32_e32 v137, 16, v239
	v_lshlrev_b32_e32 v136, 16, v243
	v_and_b32_e32 v98, 0xffff0000, v235
	v_and_b32_e32 v111, 0xffff0000, v239
	v_and_b32_e32 v110, 0xffff0000, v243
	v_lshlrev_b32_e32 v132, 16, v236
	v_lshlrev_b32_e32 v115, 16, v240
	v_lshlrev_b32_e32 v114, 16, v244
	v_lshlrev_b32_e32 v106, 16, v242
	v_and_b32_e32 v100, 0xffff0000, v236
	v_and_b32_e32 v123, 0xffff0000, v240
	v_and_b32_e32 v122, 0xffff0000, v244
	v_lshlrev_b32_e32 v134, 16, v237
	v_lshlrev_b32_e32 v139, 16, v241
	v_lshlrev_b32_e32 v138, 16, v245
	v_and_b32_e32 v102, 0xffff0000, v237
	v_add_u32_e32 v248, 0x40000, v246
	global_load_dwordx4 v[234:237], v248, s[46:47] nt
	v_and_b32_e32 v113, 0xffff0000, v241
	v_add_u32_e32 v248, 0x80000, v247
	global_load_dwordx4 v[238:241], v248, s[62:63] offset:2048 nt
	v_and_b32_e32 v112, 0xffff0000, v245
	global_load_dwordx4 v[242:245], v248, s[62:63] nt
	v_pk_mul_f32 v[96:97], v[96:97], v[108:109]
	v_pk_mul_f32 v[108:109], v[130:131], v[136:137]
	v_pk_mul_f32 v[98:99], v[98:99], v[110:111]
	v_pk_mul_f32 v[110:111], v[132:133], v[114:115]
	v_pk_mul_f32 v[106:107], v[128:129], v[106:107]
	v_pk_mul_f32 v[100:101], v[100:101], v[122:123]
	v_pk_mul_f32 v[114:115], v[134:135], v[138:139]
	v_pk_mul_f32 v[102:103], v[102:103], v[112:113]
	v_add_f32_e32 v96, v96, v97
	v_add_f32_e32 v97, v108, v109
	v_add_f32_e32 v98, v98, v99
	v_add_f32_e32 v99, v110, v111
	v_add_f32_e32 v106, v106, v107
	v_add_f32_e32 v100, v100, v101
	v_add_f32_e32 v101, v114, v115
	v_add_f32_e32 v102, v102, v103
	v_cvt_pk_bf16_f32 v96, v106, v96
	v_cvt_pk_bf16_f32 v97, v97, v98
	v_cvt_pk_bf16_f32 v98, v99, v100
	v_cvt_pk_bf16_f32 v99, v101, v102
	global_store_dwordx4 v[120:121], v[96:99], off offset:256 nt
	v_mov_b32_e32 v111, v92
	v_mov_b32_e32 v113, v94
	v_mov_b32_e32 v115, v88
	v_mov_b32_e32 v117, v90
	s_waitcnt vmcnt(11)
	v_lshlrev_b32_e32 v110, 16, v210
	s_waitcnt vmcnt(10)
	v_lshlrev_b32_e32 v121, 16, v214
	s_waitcnt vmcnt(9)
	v_lshlrev_b32_e32 v120, 16, v218
	v_and_b32_e32 v92, 0xffff0000, v210
	v_and_b32_e32 v123, 0xffff0000, v214
	v_and_b32_e32 v122, 0xffff0000, v218
	v_lshlrev_b32_e32 v112, 16, v211
	v_lshlrev_b32_e32 v125, 16, v215
	v_lshlrev_b32_e32 v124, 16, v219
	v_and_b32_e32 v94, 0xffff0000, v211
	v_and_b32_e32 v97, 0xffff0000, v215
	v_and_b32_e32 v96, 0xffff0000, v219
	v_lshlrev_b32_e32 v114, 16, v212
	v_lshlrev_b32_e32 v101, 16, v216
	v_lshlrev_b32_e32 v100, 16, v220
	v_and_b32_e32 v88, 0xffff0000, v212
	v_lshlrev_b32_e32 v116, 16, v213
	v_and_b32_e32 v90, 0xffff0000, v213
	v_add_u32_e32 v248, 0x40000, v246
	global_load_dwordx4 v[210:213], v248, s[46:47] offset:256 nt
	v_and_b32_e32 v99, 0xffff0000, v217
	v_and_b32_e32 v98, 0xffff0000, v221
	v_and_b32_e32 v107, 0xffff0000, v216
	v_and_b32_e32 v106, 0xffff0000, v220
	v_lshlrev_b32_e32 v129, 16, v217
	v_add_u32_e32 v248, 0x80000, v247
	global_load_dwordx4 v[214:217], v248, s[62:63] offset:2304 nt
	v_lshlrev_b32_e32 v128, 16, v221
	global_load_dwordx4 v[218:221], v248, s[62:63] offset:256 nt
	v_pk_mul_f32 v[102:103], v[110:111], v[120:121]
	v_pk_mul_f32 v[92:93], v[92:93], v[122:123]
	v_pk_mul_f32 v[108:109], v[112:113], v[124:125]
	v_pk_mul_f32 v[94:95], v[94:95], v[96:97]
	v_pk_mul_f32 v[96:97], v[114:115], v[100:101]
	v_pk_mul_f32 v[90:91], v[90:91], v[98:99]
	v_pk_mul_f32 v[88:89], v[88:89], v[106:107]
	v_pk_mul_f32 v[100:101], v[116:117], v[128:129]
	v_add_f32_e32 v98, v102, v103
	v_add_f32_e32 v92, v92, v93
	v_add_f32_e32 v93, v108, v109
	v_add_f32_e32 v94, v94, v95
	v_add_f32_e32 v95, v96, v97
	v_add_f32_e32 v96, v90, v91
	v_add_f32_e32 v88, v88, v89
	v_add_f32_e32 v89, v100, v101
	v_cvt_pk_bf16_f32 v90, v98, v92
	v_cvt_pk_bf16_f32 v91, v93, v94
	v_cvt_pk_bf16_f32 v92, v95, v88
	v_cvt_pk_bf16_f32 v93, v89, v96
	v_add_u32_e32 v88, 0x80, v158
	v_mov_b32_e32 v113, v80
	v_mov_b32_e32 v115, v82
	v_mov_b32_e32 v117, v84
	global_store_dwordx4 v[104:105], v[90:93], off nt
	v_ashrrev_i32_e32 v89, 31, v88
	v_mov_b32_e32 v119, v86
	v_lshlrev_b64 v[102:103], 12, v[88:89]
	v_lshlrev_b64 v[88:89], 11, v[88:89]
	v_lshl_add_u64 v[110:111], s[46:47], 0, v[88:89]
	v_lshl_add_u64 v[102:103], s[62:63], 0, v[102:103]
	v_lshl_add_u64 v[110:111], v[110:111], 0, v[156:157]
	v_lshl_add_u64 v[102:103], v[102:103], 0, v[156:157]
	v_lshl_add_u64 v[88:89], s[60:61], 0, v[88:89]
	v_lshl_add_u64 v[88:89], v[88:89], 0, v[156:157]
	s_waitcnt vmcnt(11)
	v_lshlrev_b32_e32 v112, 16, v222
	s_waitcnt vmcnt(10)
	v_lshlrev_b32_e32 v91, 16, v226
	v_and_b32_e32 v80, 0xffff0000, v222
	v_and_b32_e32 v93, 0xffff0000, v226
	s_waitcnt vmcnt(9)
	v_and_b32_e32 v92, 0xffff0000, v230
	v_lshlrev_b32_e32 v114, 16, v223
	v_lshlrev_b32_e32 v121, 16, v227
	v_lshlrev_b32_e32 v120, 16, v231
	v_and_b32_e32 v82, 0xffff0000, v223
	v_and_b32_e32 v95, 0xffff0000, v227
	v_and_b32_e32 v94, 0xffff0000, v231
	v_lshlrev_b32_e32 v116, 16, v224
	v_lshlrev_b32_e32 v99, 16, v228
	v_lshlrev_b32_e32 v98, 16, v232
	v_lshlrev_b32_e32 v90, 16, v230
	v_and_b32_e32 v84, 0xffff0000, v224
	v_and_b32_e32 v107, 0xffff0000, v228
	v_and_b32_e32 v106, 0xffff0000, v232
	v_lshlrev_b32_e32 v118, 16, v225
	v_lshlrev_b32_e32 v123, 16, v229
	v_lshlrev_b32_e32 v122, 16, v233
	v_and_b32_e32 v86, 0xffff0000, v225
	v_add_u32_e32 v248, 0x48000, v246
	global_load_dwordx4 v[222:225], v248, s[46:47] nt
	v_and_b32_e32 v97, 0xffff0000, v229
	v_add_u32_e32 v248, 0x90000, v247
	global_load_dwordx4 v[226:229], v248, s[62:63] offset:2048 nt
	v_and_b32_e32 v96, 0xffff0000, v233
	global_load_dwordx4 v[230:233], v248, s[62:63] nt
	v_pk_mul_f32 v[80:81], v[80:81], v[92:93]
	v_pk_mul_f32 v[92:93], v[114:115], v[120:121]
	v_pk_mul_f32 v[82:83], v[82:83], v[94:95]
	v_pk_mul_f32 v[94:95], v[116:117], v[98:99]
	v_pk_mul_f32 v[90:91], v[112:113], v[90:91]
	v_pk_mul_f32 v[84:85], v[84:85], v[106:107]
	v_pk_mul_f32 v[98:99], v[118:119], v[122:123]
	v_pk_mul_f32 v[86:87], v[86:87], v[96:97]
	v_add_f32_e32 v80, v80, v81
	v_add_f32_e32 v81, v92, v93
	v_add_f32_e32 v82, v82, v83
	v_add_f32_e32 v83, v94, v95
	v_add_f32_e32 v90, v90, v91
	v_add_f32_e32 v84, v84, v85
	v_add_f32_e32 v85, v98, v99
	v_add_f32_e32 v86, v86, v87
	v_cvt_pk_bf16_f32 v80, v90, v80
	v_cvt_pk_bf16_f32 v81, v81, v82
	v_cvt_pk_bf16_f32 v82, v83, v84
	v_cvt_pk_bf16_f32 v83, v85, v86
	global_store_dwordx4 v[104:105], v[80:83], off offset:256 nt
	v_mov_b32_e32 v95, v76
	v_mov_b32_e32 v97, v78
	v_mov_b32_e32 v99, v72
	v_mov_b32_e32 v101, v74
	s_waitcnt vmcnt(11)
; __device__ __forceinline__ float bf_lo(unsigned w) { return __uint_as_float(w << 16); }
; __device__ __forceinline__ float bf_hi(unsigned w) { return __uint_as_float(w & 0xffff0000u); }
; __device__ __forceinline__ u32x4 pack8(const f32x4 a, const f32x4 b) { u32x4 w; w.x = cvt_pk_bf16(a[0], a[1]); w.y = cvt_pk_bf16(a[2], a[3]); w.z = cvt_pk_bf16(b[0], b[1]); w.w = cvt_pk_bf16(b[2], b[3]); return w; }
;     __device__ __forceinline__ void operator()(const f32x4 (&acc)[2][2][4][2], const Unit& u, int wr, int wc, int fr, int fq) const {
;     ...
;         for (int ai = 0; ai < 2; ++ai)
; #pragma unroll
;             for (int m = 0; m < 4; ++m) {
;                 const size_t row = (size_t)(row0 + ai * HALF + m * 16);
; #pragma unroll
;                 for (int bj = 0; bj < 2; ++bj) {
;                     const int c = col0 + bj * HALF;
;                     const u32x4 a8 = __builtin_nontemporal_load((const u32x4*)(A + row * 1024 + c)), ga = __builtin_nontemporal_load((const u32x4*)(G + row * 2048 + c)), gp = __builtin_nontemporal_load((const u32x4*)(G + row * 2048 + 1024 + c));
;                     const f32x4 y0 = acc[ai][bj][m][0] * ps[bj][0], y1 = acc[ai][bj][m][1] * ps[bj][1];
;                     f32x4 o0, o1;
;                     o0[0] = bf_lo(ga.x) * bf_lo(a8.x) + bf_lo(gp.x) * y0[0]; o0[1] = bf_hi(ga.x) * bf_hi(a8.x) + bf_hi(gp.x) * y0[1];
;                     o0[2] = bf_lo(ga.y) * bf_lo(a8.y) + bf_lo(gp.y) * y0[2]; o0[3] = bf_hi(ga.y) * bf_hi(a8.y) + bf_hi(gp.y) * y0[3];
;                     o1[0] = bf_lo(ga.z) * bf_lo(a8.z) + bf_lo(gp.z) * y1[0]; o1[1] = bf_hi(ga.z) * bf_hi(a8.z) + bf_hi(gp.z) * y1[1];
;                     o1[2] = bf_lo(ga.w) * bf_lo(a8.w) + bf_lo(gp.w) * y1[2]; o1[3] = bf_hi(ga.w) * bf_hi(a8.w) + bf_hi(gp.w) * y1[3];
;                     __builtin_nontemporal_store(pack8(o0, o1), (u32x4*)(Mg + row * 1024 + c));
;                 }
	v_lshlrev_b32_e32 v94, 16, v234
	s_waitcnt vmcnt(10)
	v_lshlrev_b32_e32 v105, 16, v238
	s_waitcnt vmcnt(9)
	v_lshlrev_b32_e32 v104, 16, v242
	v_and_b32_e32 v76, 0xffff0000, v234
	v_and_b32_e32 v107, 0xffff0000, v238
	v_and_b32_e32 v106, 0xffff0000, v242
	v_lshlrev_b32_e32 v96, 16, v235
	v_lshlrev_b32_e32 v109, 16, v239
	v_lshlrev_b32_e32 v108, 16, v243
	v_and_b32_e32 v78, 0xffff0000, v235
	v_and_b32_e32 v81, 0xffff0000, v239
	v_and_b32_e32 v80, 0xffff0000, v243
	v_lshlrev_b32_e32 v98, 16, v236
	v_lshlrev_b32_e32 v85, 16, v240
	v_lshlrev_b32_e32 v84, 16, v244
	v_and_b32_e32 v72, 0xffff0000, v236
	v_lshlrev_b32_e32 v100, 16, v237
	v_and_b32_e32 v74, 0xffff0000, v237
	v_add_u32_e32 v248, 0x48000, v246
	global_load_dwordx4 v[234:237], v248, s[46:47] offset:256 nt
	v_and_b32_e32 v83, 0xffff0000, v241
	v_and_b32_e32 v82, 0xffff0000, v245
	v_and_b32_e32 v91, 0xffff0000, v240
	v_and_b32_e32 v90, 0xffff0000, v244
	v_lshlrev_b32_e32 v113, 16, v241
	v_add_u32_e32 v248, 0x90000, v247
	global_load_dwordx4 v[238:241], v248, s[62:63] offset:2304 nt
	v_lshlrev_b32_e32 v112, 16, v245
	global_load_dwordx4 v[242:245], v248, s[62:63] offset:256 nt
	v_pk_mul_f32 v[86:87], v[94:95], v[104:105]
	v_pk_mul_f32 v[76:77], v[76:77], v[106:107]
	v_pk_mul_f32 v[92:93], v[96:97], v[108:109]
	v_pk_mul_f32 v[78:79], v[78:79], v[80:81]
	v_pk_mul_f32 v[80:81], v[98:99], v[84:85]
	v_pk_mul_f32 v[74:75], v[74:75], v[82:83]
	v_pk_mul_f32 v[72:73], v[72:73], v[90:91]
	v_pk_mul_f32 v[84:85], v[100:101], v[112:113]
	v_add_f32_e32 v82, v86, v87
	v_add_f32_e32 v76, v76, v77
	v_add_f32_e32 v77, v92, v93
	v_add_f32_e32 v78, v78, v79
	v_add_f32_e32 v79, v80, v81
	v_add_f32_e32 v80, v74, v75
	v_add_f32_e32 v72, v72, v73
	v_add_f32_e32 v73, v84, v85
	v_cvt_pk_bf16_f32 v74, v82, v76
	v_cvt_pk_bf16_f32 v75, v77, v78
	v_cvt_pk_bf16_f32 v76, v79, v72
	v_cvt_pk_bf16_f32 v77, v73, v80
	v_add_u32_e32 v72, 0x90, v158
	v_mov_b32_e32 v97, v64
	v_mov_b32_e32 v99, v66
	v_mov_b32_e32 v101, v68
	global_store_dwordx4 v[88:89], v[74:77], off nt
	v_ashrrev_i32_e32 v73, 31, v72
	v_mov_b32_e32 v103, v70
	v_lshlrev_b64 v[86:87], 12, v[72:73]
	v_lshlrev_b64 v[72:73], 11, v[72:73]
	v_lshl_add_u64 v[94:95], s[46:47], 0, v[72:73]
	v_lshl_add_u64 v[86:87], s[62:63], 0, v[86:87]
	v_lshl_add_u64 v[94:95], v[94:95], 0, v[156:157]
	v_lshl_add_u64 v[86:87], v[86:87], 0, v[156:157]
	v_lshl_add_u64 v[72:73], s[60:61], 0, v[72:73]
	v_lshl_add_u64 v[72:73], v[72:73], 0, v[156:157]
	s_waitcnt vmcnt(11)
	v_lshlrev_b32_e32 v96, 16, v210
	s_waitcnt vmcnt(10)
	v_lshlrev_b32_e32 v75, 16, v214
	v_and_b32_e32 v64, 0xffff0000, v210
	v_and_b32_e32 v77, 0xffff0000, v214
	s_waitcnt vmcnt(9)
	v_and_b32_e32 v76, 0xffff0000, v218
	v_lshlrev_b32_e32 v98, 16, v211
	v_lshlrev_b32_e32 v105, 16, v215
	v_lshlrev_b32_e32 v104, 16, v219
	v_and_b32_e32 v66, 0xffff0000, v211
	v_and_b32_e32 v79, 0xffff0000, v215
	v_and_b32_e32 v78, 0xffff0000, v219
	v_lshlrev_b32_e32 v100, 16, v212
	v_lshlrev_b32_e32 v83, 16, v216
	v_lshlrev_b32_e32 v82, 16, v220
	v_lshlrev_b32_e32 v74, 16, v218
	v_and_b32_e32 v68, 0xffff0000, v212
	v_and_b32_e32 v91, 0xffff0000, v216
	v_and_b32_e32 v90, 0xffff0000, v220
	v_lshlrev_b32_e32 v102, 16, v213
	v_lshlrev_b32_e32 v107, 16, v217
	v_lshlrev_b32_e32 v106, 16, v221
	v_and_b32_e32 v70, 0xffff0000, v213
	v_add_u32_e32 v248, 0x50000, v246
	global_load_dwordx4 v[210:213], v248, s[46:47] nt
	v_and_b32_e32 v81, 0xffff0000, v217
	v_add_u32_e32 v248, 0xa0000, v247
	global_load_dwordx4 v[214:217], v248, s[62:63] offset:2048 nt
	v_and_b32_e32 v80, 0xffff0000, v221
	global_load_dwordx4 v[218:221], v248, s[62:63] nt
	v_pk_mul_f32 v[64:65], v[64:65], v[76:77]
	v_pk_mul_f32 v[76:77], v[98:99], v[104:105]
	v_pk_mul_f32 v[66:67], v[66:67], v[78:79]
	v_pk_mul_f32 v[78:79], v[100:101], v[82:83]
	v_pk_mul_f32 v[74:75], v[96:97], v[74:75]
	v_pk_mul_f32 v[68:69], v[68:69], v[90:91]
	v_pk_mul_f32 v[82:83], v[102:103], v[106:107]
	v_pk_mul_f32 v[70:71], v[70:71], v[80:81]
	v_add_f32_e32 v64, v64, v65
	v_add_f32_e32 v65, v76, v77
	v_add_f32_e32 v66, v66, v67
	v_add_f32_e32 v67, v78, v79
	v_add_f32_e32 v74, v74, v75
	v_add_f32_e32 v68, v68, v69
	v_add_f32_e32 v69, v82, v83
	v_add_f32_e32 v70, v70, v71
	v_cvt_pk_bf16_f32 v64, v74, v64
	v_cvt_pk_bf16_f32 v65, v65, v66
	v_cvt_pk_bf16_f32 v66, v67, v68
	v_cvt_pk_bf16_f32 v67, v69, v70
	global_store_dwordx4 v[88:89], v[64:67], off offset:256 nt
	v_mov_b32_e32 v79, v60
	v_mov_b32_e32 v81, v62
	v_mov_b32_e32 v83, v56
	v_mov_b32_e32 v85, v58
	s_waitcnt vmcnt(11)
	v_lshlrev_b32_e32 v78, 16, v222
	s_waitcnt vmcnt(10)
	v_lshlrev_b32_e32 v89, 16, v226
	s_waitcnt vmcnt(9)
; __device__ __forceinline__ float bf_lo(unsigned w) { return __uint_as_float(w << 16); }
; __device__ __forceinline__ float bf_hi(unsigned w) { return __uint_as_float(w & 0xffff0000u); }
; __device__ __forceinline__ u32x4 pack8(const f32x4 a, const f32x4 b) { u32x4 w; w.x = cvt_pk_bf16(a[0], a[1]); w.y = cvt_pk_bf16(a[2], a[3]); w.z = cvt_pk_bf16(b[0], b[1]); w.w = cvt_pk_bf16(b[2], b[3]); return w; }
;     __device__ __forceinline__ void operator()(const f32x4 (&acc)[2][2][4][2], const Unit& u, int wr, int wc, int fr, int fq) const {
;     ...
;         for (int ai = 0; ai < 2; ++ai)
; #pragma unroll
;             for (int m = 0; m < 4; ++m) {
;                 const size_t row = (size_t)(row0 + ai * HALF + m * 16);
; #pragma unroll
;                 for (int bj = 0; bj < 2; ++bj) {
;                     const int c = col0 + bj * HALF;
;                     const u32x4 a8 = __builtin_nontemporal_load((const u32x4*)(A + row * 1024 + c)), ga = __builtin_nontemporal_load((const u32x4*)(G + row * 2048 + c)), gp = __builtin_nontemporal_load((const u32x4*)(G + row * 2048 + 1024 + c));
;                     const f32x4 y0 = acc[ai][bj][m][0] * ps[bj][0], y1 = acc[ai][bj][m][1] * ps[bj][1];
;                     f32x4 o0, o1;
;                     o0[0] = bf_lo(ga.x) * bf_lo(a8.x) + bf_lo(gp.x) * y0[0]; o0[1] = bf_hi(ga.x) * bf_hi(a8.x) + bf_hi(gp.x) * y0[1];
;                     o0[2] = bf_lo(ga.y) * bf_lo(a8.y) + bf_lo(gp.y) * y0[2]; o0[3] = bf_hi(ga.y) * bf_hi(a8.y) + bf_hi(gp.y) * y0[3];
;                     o1[0] = bf_lo(ga.z) * bf_lo(a8.z) + bf_lo(gp.z) * y1[0]; o1[1] = bf_hi(ga.z) * bf_hi(a8.z) + bf_hi(gp.z) * y1[1];
;                     o1[2] = bf_lo(ga.w) * bf_lo(a8.w) + bf_lo(gp.w) * y1[2]; o1[3] = bf_hi(ga.w) * bf_hi(a8.w) + bf_hi(gp.w) * y1[3];
;                     __builtin_nontemporal_store(pack8(o0, o1), (u32x4*)(Mg + row * 1024 + c));
;                 }
	v_lshlrev_b32_e32 v88, 16, v230
	v_and_b32_e32 v60, 0xffff0000, v222
	v_and_b32_e32 v91, 0xffff0000, v226
	v_and_b32_e32 v90, 0xffff0000, v230
	v_lshlrev_b32_e32 v80, 16, v223
	v_lshlrev_b32_e32 v93, 16, v227
	v_lshlrev_b32_e32 v92, 16, v231
	v_and_b32_e32 v62, 0xffff0000, v223
	v_and_b32_e32 v65, 0xffff0000, v227
	v_and_b32_e32 v64, 0xffff0000, v231
	v_lshlrev_b32_e32 v82, 16, v224
	v_lshlrev_b32_e32 v69, 16, v228
	v_lshlrev_b32_e32 v68, 16, v232
	v_and_b32_e32 v56, 0xffff0000, v224
	v_lshlrev_b32_e32 v84, 16, v225
	v_and_b32_e32 v58, 0xffff0000, v225
	v_add_u32_e32 v248, 0x50000, v246
	global_load_dwordx4 v[222:225], v248, s[46:47] offset:256 nt
	v_and_b32_e32 v67, 0xffff0000, v229
	v_and_b32_e32 v66, 0xffff0000, v233
	v_and_b32_e32 v75, 0xffff0000, v228
	v_and_b32_e32 v74, 0xffff0000, v232
	v_lshlrev_b32_e32 v97, 16, v229
	v_add_u32_e32 v248, 0xa0000, v247
	global_load_dwordx4 v[226:229], v248, s[62:63] offset:2304 nt
	v_lshlrev_b32_e32 v96, 16, v233
	global_load_dwordx4 v[230:233], v248, s[62:63] offset:256 nt
	v_pk_mul_f32 v[70:71], v[78:79], v[88:89]
	v_pk_mul_f32 v[60:61], v[60:61], v[90:91]
	v_pk_mul_f32 v[76:77], v[80:81], v[92:93]
	v_pk_mul_f32 v[62:63], v[62:63], v[64:65]
	v_pk_mul_f32 v[64:65], v[82:83], v[68:69]
	v_pk_mul_f32 v[58:59], v[58:59], v[66:67]
	v_pk_mul_f32 v[56:57], v[56:57], v[74:75]
	v_pk_mul_f32 v[68:69], v[84:85], v[96:97]
	v_add_f32_e32 v66, v70, v71
	v_add_f32_e32 v60, v60, v61
	v_add_f32_e32 v61, v76, v77
	v_add_f32_e32 v62, v62, v63
	v_add_f32_e32 v63, v64, v65
	v_add_f32_e32 v64, v58, v59
	v_add_f32_e32 v56, v56, v57
	v_add_f32_e32 v57, v68, v69
	v_cvt_pk_bf16_f32 v58, v66, v60
	v_cvt_pk_bf16_f32 v59, v61, v62
	v_cvt_pk_bf16_f32 v60, v63, v56
	v_cvt_pk_bf16_f32 v61, v57, v64
	v_add_u32_e32 v56, 0xa0, v158
	v_mov_b32_e32 v81, v48
	v_mov_b32_e32 v83, v50
	v_mov_b32_e32 v85, v52
	global_store_dwordx4 v[72:73], v[58:61], off nt
	v_ashrrev_i32_e32 v57, 31, v56
	v_mov_b32_e32 v87, v54
	v_lshlrev_b64 v[70:71], 12, v[56:57]
	v_lshlrev_b64 v[56:57], 11, v[56:57]
	v_lshl_add_u64 v[78:79], s[46:47], 0, v[56:57]
	v_lshl_add_u64 v[70:71], s[62:63], 0, v[70:71]
	v_lshl_add_u64 v[78:79], v[78:79], 0, v[156:157]
	v_lshl_add_u64 v[70:71], v[70:71], 0, v[156:157]
	v_lshl_add_u64 v[56:57], s[60:61], 0, v[56:57]
	v_lshl_add_u64 v[56:57], v[56:57], 0, v[156:157]
	s_waitcnt vmcnt(11)
	v_lshlrev_b32_e32 v80, 16, v234
	s_waitcnt vmcnt(10)
	v_lshlrev_b32_e32 v59, 16, v238
	v_and_b32_e32 v48, 0xffff0000, v234
	v_and_b32_e32 v61, 0xffff0000, v238
	s_waitcnt vmcnt(9)
	v_and_b32_e32 v60, 0xffff0000, v242
	v_lshlrev_b32_e32 v82, 16, v235
	v_lshlrev_b32_e32 v89, 16, v239
	v_lshlrev_b32_e32 v88, 16, v243
	v_and_b32_e32 v50, 0xffff0000, v235
	v_and_b32_e32 v63, 0xffff0000, v239
	v_and_b32_e32 v62, 0xffff0000, v243
	v_lshlrev_b32_e32 v84, 16, v236
	v_lshlrev_b32_e32 v67, 16, v240
	v_lshlrev_b32_e32 v66, 16, v244
	v_lshlrev_b32_e32 v58, 16, v242
	v_and_b32_e32 v52, 0xffff0000, v236
	v_and_b32_e32 v75, 0xffff0000, v240
	v_and_b32_e32 v74, 0xffff0000, v244
	v_lshlrev_b32_e32 v86, 16, v237
	v_lshlrev_b32_e32 v91, 16, v241
	v_lshlrev_b32_e32 v90, 16, v245
	v_and_b32_e32 v54, 0xffff0000, v237
	v_add_u32_e32 v248, 0x58000, v246
	global_load_dwordx4 v[234:237], v248, s[46:47] nt
	v_and_b32_e32 v65, 0xffff0000, v241
	v_add_u32_e32 v248, 0xb0000, v247
	global_load_dwordx4 v[238:241], v248, s[62:63] offset:2048 nt
	v_and_b32_e32 v64, 0xffff0000, v245
	global_load_dwordx4 v[242:245], v248, s[62:63] nt
	v_pk_mul_f32 v[48:49], v[48:49], v[60:61]
	v_pk_mul_f32 v[60:61], v[82:83], v[88:89]
	v_pk_mul_f32 v[50:51], v[50:51], v[62:63]
	v_pk_mul_f32 v[62:63], v[84:85], v[66:67]
	v_pk_mul_f32 v[58:59], v[80:81], v[58:59]
	v_pk_mul_f32 v[52:53], v[52:53], v[74:75]
	v_pk_mul_f32 v[66:67], v[86:87], v[90:91]
	v_pk_mul_f32 v[54:55], v[54:55], v[64:65]
	v_add_f32_e32 v48, v48, v49
	v_add_f32_e32 v49, v60, v61
	v_add_f32_e32 v50, v50, v51
	v_add_f32_e32 v51, v62, v63
	v_add_f32_e32 v58, v58, v59
	v_add_f32_e32 v52, v52, v53
	v_add_f32_e32 v53, v66, v67
	v_add_f32_e32 v54, v54, v55
	v_cvt_pk_bf16_f32 v48, v58, v48
	v_cvt_pk_bf16_f32 v49, v49, v50
	v_cvt_pk_bf16_f32 v50, v51, v52
	v_cvt_pk_bf16_f32 v51, v53, v54
	global_store_dwordx4 v[72:73], v[48:51], off offset:256 nt
	v_mov_b32_e32 v63, v44
	v_mov_b32_e32 v65, v46
	v_mov_b32_e32 v67, v40
	v_mov_b32_e32 v69, v42
	s_waitcnt vmcnt(11)
	v_lshlrev_b32_e32 v62, 16, v210
	s_waitcnt vmcnt(10)
	v_lshlrev_b32_e32 v73, 16, v214
	s_waitcnt vmcnt(9)
	v_lshlrev_b32_e32 v72, 16, v218
	v_and_b32_e32 v44, 0xffff0000, v210
	v_and_b32_e32 v75, 0xffff0000, v214
	v_and_b32_e32 v74, 0xffff0000, v218
	v_lshlrev_b32_e32 v64, 16, v211
	v_lshlrev_b32_e32 v77, 16, v215
	v_lshlrev_b32_e32 v76, 16, v219
	v_and_b32_e32 v46, 0xffff0000, v211
	v_and_b32_e32 v49, 0xffff0000, v215
	v_and_b32_e32 v48, 0xffff0000, v219
	v_lshlrev_b32_e32 v66, 16, v212
	v_lshlrev_b32_e32 v53, 16, v216
	v_lshlrev_b32_e32 v52, 16, v220
	v_and_b32_e32 v40, 0xffff0000, v212
	v_and_b32_e32 v59, 0xffff0000, v216
	v_and_b32_e32 v58, 0xffff0000, v220
	v_lshlrev_b32_e32 v68, 16, v213
	v_lshlrev_b32_e32 v81, 16, v217
	v_lshlrev_b32_e32 v80, 16, v221
	v_and_b32_e32 v42, 0xffff0000, v213
	v_add_u32_e32 v248, 0x58000, v246
	global_load_dwordx4 v[210:213], v248, s[46:47] offset:256 nt
	v_and_b32_e32 v51, 0xffff0000, v217
	v_add_u32_e32 v248, 0xb0000, v247
	global_load_dwordx4 v[214:217], v248, s[62:63] offset:2304 nt
	v_and_b32_e32 v50, 0xffff0000, v221
	global_load_dwordx4 v[218:221], v248, s[62:63] offset:256 nt
	v_pk_mul_f32 v[54:55], v[62:63], v[72:73]
	v_pk_mul_f32 v[44:45], v[44:45], v[74:75]
	v_pk_mul_f32 v[60:61], v[64:65], v[76:77]
	v_pk_mul_f32 v[46:47], v[46:47], v[48:49]
	v_pk_mul_f32 v[48:49], v[66:67], v[52:53]
	v_pk_mul_f32 v[40:41], v[40:41], v[58:59]
	v_pk_mul_f32 v[52:53], v[68:69], v[80:81]
	v_pk_mul_f32 v[42:43], v[42:43], v[50:51]
	v_add_f32_e32 v50, v54, v55
	v_add_f32_e32 v44, v44, v45
	v_add_f32_e32 v45, v60, v61
	v_add_f32_e32 v46, v46, v47
	v_add_f32_e32 v47, v48, v49
	v_add_f32_e32 v48, v40, v41
	v_add_f32_e32 v49, v52, v53
	v_add_f32_e32 v43, v42, v43
	v_cvt_pk_bf16_f32 v40, v50, v44
	v_cvt_pk_bf16_f32 v41, v45, v46
	v_cvt_pk_bf16_f32 v42, v47, v48
	v_cvt_pk_bf16_f32 v43, v49, v43
	v_add_u32_e32 v58, 0xb0, v158
	v_mov_b32_e32 v65, v32
	v_mov_b32_e32 v67, v34
	v_mov_b32_e32 v69, v36
	global_store_dwordx4 v[56:57], v[40:43], off nt
	v_ashrrev_i32_e32 v59, 31, v58
	v_mov_b32_e32 v71, v38
	v_lshlrev_b64 v[60:61], 12, v[58:59]
	v_lshlrev_b64 v[58:59], 11, v[58:59]
	v_lshl_add_u64 v[62:63], s[46:47], 0, v[58:59]
	v_lshl_add_u64 v[60:61], s[62:63], 0, v[60:61]
	v_lshl_add_u64 v[62:63], v[62:63], 0, v[156:157]
	v_lshl_add_u64 v[60:61], v[60:61], 0, v[156:157]
	s_waitcnt vmcnt(11)
; __device__ __forceinline__ float bf_lo(unsigned w) { return __uint_as_float(w << 16); }
; __device__ __forceinline__ float bf_hi(unsigned w) { return __uint_as_float(w & 0xffff0000u); }
; __device__ __forceinline__ u32x4 pack8(const f32x4 a, const f32x4 b) { u32x4 w; w.x = cvt_pk_bf16(a[0], a[1]); w.y = cvt_pk_bf16(a[2], a[3]); w.z = cvt_pk_bf16(b[0], b[1]); w.w = cvt_pk_bf16(b[2], b[3]); return w; }
;     __device__ __forceinline__ void operator()(const f32x4 (&acc)[2][2][4][2], const Unit& u, int wr, int wc, int fr, int fq) const {
;     ...
;         for (int ai = 0; ai < 2; ++ai)
; #pragma unroll
;             for (int m = 0; m < 4; ++m) {
;                 const size_t row = (size_t)(row0 + ai * HALF + m * 16);
; #pragma unroll
;                 for (int bj = 0; bj < 2; ++bj) {
;                     const int c = col0 + bj * HALF;
;                     const u32x4 a8 = __builtin_nontemporal_load((const u32x4*)(A + row * 1024 + c)), ga = __builtin_nontemporal_load((const u32x4*)(G + row * 2048 + c)), gp = __builtin_nontemporal_load((const u32x4*)(G + row * 2048 + 1024 + c));
;                     const f32x4 y0 = acc[ai][bj][m][0] * ps[bj][0], y1 = acc[ai][bj][m][1] * ps[bj][1];
;                     f32x4 o0, o1;
;                     o0[0] = bf_lo(ga.x) * bf_lo(a8.x) + bf_lo(gp.x) * y0[0]; o0[1] = bf_hi(ga.x) * bf_hi(a8.x) + bf_hi(gp.x) * y0[1];
;                     o0[2] = bf_lo(ga.y) * bf_lo(a8.y) + bf_lo(gp.y) * y0[2]; o0[3] = bf_hi(ga.y) * bf_hi(a8.y) + bf_hi(gp.y) * y0[3];
;                     o1[0] = bf_lo(ga.z) * bf_lo(a8.z) + bf_lo(gp.z) * y1[0]; o1[1] = bf_hi(ga.z) * bf_hi(a8.z) + bf_hi(gp.z) * y1[1];
;                     o1[2] = bf_lo(ga.w) * bf_lo(a8.w) + bf_lo(gp.w) * y1[2]; o1[3] = bf_hi(ga.w) * bf_hi(a8.w) + bf_hi(gp.w) * y1[3];
;                     __builtin_nontemporal_store(pack8(o0, o1), (u32x4*)(Mg + row * 1024 + c));
;                 }
	v_lshlrev_b32_e32 v64, 16, v222
	s_waitcnt vmcnt(10)
	v_lshlrev_b32_e32 v41, 16, v226
	v_and_b32_e32 v32, 0xffff0000, v222
	v_and_b32_e32 v43, 0xffff0000, v226
	s_waitcnt vmcnt(9)
	v_and_b32_e32 v42, 0xffff0000, v230
	v_lshlrev_b32_e32 v66, 16, v223
	v_lshlrev_b32_e32 v73, 16, v227
	v_lshlrev_b32_e32 v72, 16, v231
	v_and_b32_e32 v34, 0xffff0000, v223
	v_and_b32_e32 v45, 0xffff0000, v227
	v_and_b32_e32 v44, 0xffff0000, v231
	v_lshlrev_b32_e32 v68, 16, v224
	v_lshlrev_b32_e32 v49, 16, v228
	v_lshlrev_b32_e32 v48, 16, v232
	v_lshlrev_b32_e32 v40, 16, v230
	v_and_b32_e32 v36, 0xffff0000, v224
	v_and_b32_e32 v53, 0xffff0000, v228
	v_and_b32_e32 v52, 0xffff0000, v232
	v_lshlrev_b32_e32 v70, 16, v225
	v_lshlrev_b32_e32 v75, 16, v229
	v_lshlrev_b32_e32 v74, 16, v233
	v_and_b32_e32 v38, 0xffff0000, v225
	v_and_b32_e32 v47, 0xffff0000, v229
	v_and_b32_e32 v46, 0xffff0000, v233
	v_pk_mul_f32 v[32:33], v[32:33], v[42:43]
	v_pk_mul_f32 v[42:43], v[66:67], v[72:73]
	v_pk_mul_f32 v[34:35], v[34:35], v[44:45]
	v_pk_mul_f32 v[44:45], v[68:69], v[48:49]
	v_pk_mul_f32 v[40:41], v[64:65], v[40:41]
	v_pk_mul_f32 v[36:37], v[36:37], v[52:53]
	v_pk_mul_f32 v[48:49], v[70:71], v[74:75]
	v_pk_mul_f32 v[38:39], v[38:39], v[46:47]
	v_add_f32_e32 v32, v32, v33
	v_add_f32_e32 v33, v42, v43
	v_add_f32_e32 v34, v34, v35
	v_add_f32_e32 v35, v44, v45
	v_add_f32_e32 v40, v40, v41
	v_add_f32_e32 v36, v36, v37
	v_add_f32_e32 v37, v48, v49
	v_add_f32_e32 v38, v38, v39
	v_cvt_pk_bf16_f32 v32, v40, v32
	v_cvt_pk_bf16_f32 v33, v33, v34
	v_cvt_pk_bf16_f32 v34, v35, v36
	v_cvt_pk_bf16_f32 v35, v37, v38
	global_store_dwordx4 v[56:57], v[32:35], off offset:256 nt
	s_waitcnt vmcnt(8)
	v_lshlrev_b32_e32 v24, 16, v234
	s_waitcnt vmcnt(7)
	v_lshlrev_b32_e32 v45, 16, v238
	s_waitcnt vmcnt(6)
	v_lshlrev_b32_e32 v44, 16, v242
	v_and_b32_e32 v20, 0xffff0000, v234
	v_and_b32_e32 v47, 0xffff0000, v238
	v_and_b32_e32 v46, 0xffff0000, v242
	v_lshlrev_b32_e32 v26, 16, v235
	v_lshlrev_b32_e32 v49, 16, v239
	v_lshlrev_b32_e32 v48, 16, v243
	v_and_b32_e32 v22, 0xffff0000, v235
	v_and_b32_e32 v33, 0xffff0000, v239
	v_and_b32_e32 v32, 0xffff0000, v243
	v_lshlrev_b32_e32 v28, 16, v236
	v_lshlrev_b32_e32 v37, 16, v240
	v_lshlrev_b32_e32 v36, 16, v244
	v_and_b32_e32 v16, 0xffff0000, v236
	v_and_b32_e32 v41, 0xffff0000, v240
	v_and_b32_e32 v40, 0xffff0000, v244
	v_lshlrev_b32_e32 v30, 16, v237
	v_lshlrev_b32_e32 v51, 16, v241
	v_lshlrev_b32_e32 v50, 16, v245
	v_and_b32_e32 v18, 0xffff0000, v237
	v_and_b32_e32 v35, 0xffff0000, v241
	v_and_b32_e32 v34, 0xffff0000, v245
	v_pk_mul_f32 v[24:25], v[24:25], v[44:45]
	v_pk_mul_f32 v[20:21], v[20:21], v[46:47]
	v_pk_mul_f32 v[26:27], v[26:27], v[48:49]
	v_pk_mul_f32 v[22:23], v[22:23], v[32:33]
	v_pk_mul_f32 v[28:29], v[28:29], v[36:37]
	v_pk_mul_f32 v[16:17], v[16:17], v[40:41]
	v_pk_mul_f32 v[30:31], v[30:31], v[50:51]
	v_pk_mul_f32 v[18:19], v[18:19], v[34:35]
	v_add_f32_e32 v24, v24, v25
	v_add_f32_e32 v20, v20, v21
	v_add_f32_e32 v21, v26, v27
	v_add_f32_e32 v22, v22, v23
	v_add_f32_e32 v23, v28, v29
	v_add_f32_e32 v25, v16, v17
	v_add_f32_e32 v26, v30, v31
	v_add_f32_e32 v19, v18, v19
	v_cvt_pk_bf16_f32 v16, v24, v20
	v_cvt_pk_bf16_f32 v17, v21, v22
	v_cvt_pk_bf16_f32 v18, v23, v25
	v_cvt_pk_bf16_f32 v19, v26, v19
	v_lshl_add_u64 v[32:33], s[60:61], 0, v[58:59]
	v_lshl_add_u64 v[32:33], v[32:33], 0, v[156:157]
	global_store_dwordx4 v[32:33], v[16:19], off nt
	s_waitcnt vmcnt(5)
	v_lshlrev_b32_e32 v12, 16, v212
	v_and_b32_e32 v0, 0xffff0000, v212
	v_lshlrev_b32_e32 v14, 16, v213
	v_and_b32_e32 v2, 0xffff0000, v213
	s_waitcnt vmcnt(4)
	v_and_b32_e32 v23, 0xffff0000, v217
	s_waitcnt vmcnt(3)
	v_and_b32_e32 v22, 0xffff0000, v221
	v_lshlrev_b32_e32 v8, 16, v210
	v_lshlrev_b32_e32 v17, 16, v214
	v_lshlrev_b32_e32 v16, 16, v218
	v_and_b32_e32 v4, 0xffff0000, v210
	v_and_b32_e32 v19, 0xffff0000, v214
	v_and_b32_e32 v18, 0xffff0000, v218
	v_lshlrev_b32_e32 v10, 16, v211
	v_lshlrev_b32_e32 v35, 16, v215
	v_lshlrev_b32_e32 v34, 16, v219
	v_and_b32_e32 v6, 0xffff0000, v211
	v_and_b32_e32 v21, 0xffff0000, v215
	v_and_b32_e32 v20, 0xffff0000, v219
	v_lshlrev_b32_e32 v25, 16, v216
	v_lshlrev_b32_e32 v24, 16, v220
	v_and_b32_e32 v29, 0xffff0000, v216
	v_and_b32_e32 v28, 0xffff0000, v220
	v_lshlrev_b32_e32 v37, 16, v217
	v_lshlrev_b32_e32 v36, 16, v221
	v_pk_mul_f32 v[2:3], v[2:3], v[22:23]
	v_pk_mul_f32 v[8:9], v[8:9], v[16:17]
	v_pk_mul_f32 v[4:5], v[4:5], v[18:19]
	v_pk_mul_f32 v[10:11], v[10:11], v[34:35]
	v_pk_mul_f32 v[6:7], v[6:7], v[20:21]
	v_pk_mul_f32 v[12:13], v[12:13], v[24:25]
	v_pk_mul_f32 v[0:1], v[0:1], v[28:29]
	v_pk_mul_f32 v[14:15], v[14:15], v[36:37]
	v_add_f32_e32 v3, v2, v3
	v_add_f32_e32 v8, v8, v9
	v_add_f32_e32 v4, v4, v5
	v_add_f32_e32 v5, v10, v11
	v_add_f32_e32 v6, v6, v7
	v_add_f32_e32 v7, v12, v13
	v_add_f32_e32 v9, v0, v1
	v_add_f32_e32 v10, v14, v15
	v_cvt_pk_bf16_f32 v0, v8, v4
	v_cvt_pk_bf16_f32 v1, v5, v6
	v_cvt_pk_bf16_f32 v2, v7, v9
	v_cvt_pk_bf16_f32 v3, v10, v3
	global_store_dwordx4 v[32:33], v[0:3], off offset:256 nt
	s_cbranch_vccnz .LBB0_372
	s_andn2_b64 vcc, exec, s[4:5]
	s_cbranch_vccnz .LBB0_371
	s_barrier
	s_branch .LBB0_371

; template <int K> __device__ __forceinline__ float xor_swz(float v) { return __int_as_float(__builtin_amdgcn_ds_swizzle(__float_as_int(v), (K << 10) | 0x1f)); }
; __device__ __forceinline__ float half_sum(float v) { auto rr = __builtin_amdgcn_permlane32_swap(__float_as_uint(v), __float_as_uint(v), false, false); return __uint_as_float(rr[0]) + __uint_as_float(rr[1]); }
; __device__ __forceinline__ unsigned cvt_pk_bf16(float lo, float hi) { unsigned r; asm volatile("v_cvt_pk_bf16_f32 %0, %1, %2" : "=v"(r) : "v"(lo), "v"(hi)); return r; }
;     __device__ __forceinline__ void operator()(const f32x4 (&acc)[2][2][4][2], const Unit& u, int wr, int wc, int fr, int fq) const {
;     ...
;         const int row0 = u.pm * BM + wr * 64 + fr, col0 = u.pn * BM + wc * 32 + 8 * fq;
; #pragma unroll
;         for (int ai = 0; ai < 2; ++ai)
; #pragma unroll
;             for (int m = 0; m < 4; ++m) {
;                 const size_t row = (size_t)(row0 + ai * HALF + m * 16);
;                 const f32x4 pq = *(const f32x4*)(ssq + row * 16 + 4 * fq);
;                 float s = (pq[0] + pq[1]) + (pq[2] + pq[3]); s += xor_swz<16>(s); s = half_sum(s);
;                 const float r2 = __builtin_amdgcn_rcpf(s * (1.0f / 1024.0f) + 1e-6f);
;                 const f32x2v r2v = {r2, r2};
; #pragma unroll
;                 for (int bj = 0; bj < 2; ++bj) {
;                     f32x4 v0 = acc[ai][bj][m][0], v1 = acc[ai][bj][m][1];
; #pragma unroll
;                     for (int e = 0; e < 4; ++e) { v0[e] = fmaxf(v0[e], 0.f); v1[e] = fmaxf(v1[e], 0.f); }
;                     f32x2v a = {v0[0], v0[1]}, b = {v0[2], v0[3]}, c = {v1[0], v1[1]}, d = {v1[2], v1[3]};
;                     a = (a * a) * r2v; b = (b * b) * r2v; c = (c * c) * r2v; d = (d * d) * r2v;
;                     u32x4 w; w.x = cvt_pk_bf16(a.x, a.y); w.y = cvt_pk_bf16(b.x, b.y); w.z = cvt_pk_bf16(c.x, c.y); w.w = cvt_pk_bf16(d.x, d.y);
;                     __builtin_nontemporal_store(w, (u32x4*)(Z + row * 4096 + col0 + bj * HALF));
.LBB0_465:
	v_mbcnt_lo_u32_b32 v200, -1, 0
	v_mbcnt_hi_u32_b32 v200, -1, v200
	v_lshrrev_b32_e32 v201, 2, v200
	v_and_b32_e32 v200, 3, v200
	v_lshl_or_b32 v200, v200, 4, v201
	v_lshlrev_b32_e32 v200, 2, v200
	v_lshl_add_u32 v146, s22, 8, v148
	v_ashrrev_i32_e32 v147, 31, v146
	v_lshlrev_b64 v[156:157], 6, v[146:147]
	v_lshl_add_u64 v[156:157], v[136:137], 0, v[156:157]
	global_load_dwordx4 v[156:159], v[156:157], off
	v_lshl_or_b32 v160, s40, 8, v150
	v_max_f32_e32 v124, v124, v124
	v_max_f32_e32 v125, v125, v125
	v_max_f32_e32 v126, v126, v126
	v_max_f32_e32 v162, v112, v112
	v_max_f32_e32 v164, v113, v113
	v_max_f32_e32 v166, v114, v114
	v_max_f32_e32 v167, v119, v119
	v_ashrrev_i32_e32 v161, 31, v160
	v_max_f32_e32 v112, 0, v124
	v_max_f32_e32 v113, 0, v125
	v_max_f32_e32 v155, v116, v116
	v_max_f32_e32 v116, 0, v126
	v_max_f32_e32 v126, 0, v166
	v_max_f32_e32 v125, 0, v167
	v_pk_mul_f32 v[166:167], v[112:113], v[112:113]
	v_lshlrev_b64 v[112:113], 1, v[160:161]
	v_max_f32_e32 v123, v123, v123
	v_max_f32_e32 v165, v118, v118
	v_max_f32_e32 v120, v120, v120
	v_max_f32_e32 v119, 0, v123
	v_max_f32_e32 v123, 0, v164
	v_max_f32_e32 v124, 0, v165
	v_lshlrev_b64 v[164:165], 13, v[146:147]
	v_max_f32_e32 v114, 0, v120
	v_max_f32_e32 v120, 0, v155
	v_max_f32_e32 v127, v127, v127
	v_max_f32_e32 v121, v121, v121
	v_max_f32_e32 v122, v122, v122
	v_max_f32_e32 v163, v117, v117
	v_max_f32_e32 v117, 0, v127
	v_max_f32_e32 v168, v115, v115
	v_max_f32_e32 v115, 0, v121
	v_max_f32_e32 v118, 0, v122
	v_max_f32_e32 v122, 0, v162
	v_or_b32_e32 v162, 16, v146
	v_pk_mul_f32 v[116:117], v[116:117], v[116:117]
	v_max_f32_e32 v121, 0, v163
	v_max_f32_e32 v127, 0, v168
	v_pk_mul_f32 v[118:119], v[118:119], v[118:119]
	v_pk_mul_f32 v[114:115], v[114:115], v[114:115]
	v_ashrrev_i32_e32 v163, 31, v162
	v_pk_mul_f32 v[124:125], v[124:125], v[124:125]
	v_pk_mul_f32 v[120:121], v[120:121], v[120:121]
	v_pk_mul_f32 v[126:127], v[126:127], v[126:127]
	v_pk_mul_f32 v[122:123], v[122:123], v[122:123]
	v_max_f32_e32 v105, v105, v105
	v_max_f32_e32 v107, v107, v107
	v_max_f32_e32 v108, v108, v108
	v_max_f32_e32 v104, v104, v104
	v_max_f32_e32 v109, v109, v109
	v_max_f32_e32 v110, v110, v110
	v_max_f32_e32 v106, v106, v106
	v_max_f32_e32 v111, v111, v111
	v_max_f32_e32 v89, v89, v89
	v_max_f32_e32 v91, v91, v91
	v_max_f32_e32 v92, v92, v92
	v_max_f32_e32 v88, v88, v88
	v_max_f32_e32 v93, v93, v93
	v_max_f32_e32 v94, v94, v94
	v_max_f32_e32 v90, v90, v90
	v_max_f32_e32 v95, v95, v95
	v_max_f32_e32 v73, v73, v73
	v_max_f32_e32 v75, v75, v75
	v_max_f32_e32 v76, v76, v76
	v_max_f32_e32 v72, v72, v72
	v_max_f32_e32 v77, v77, v77
	v_max_f32_e32 v78, v78, v78
	v_max_f32_e32 v74, v74, v74
	v_max_f32_e32 v79, v79, v79
	v_max_f32_e32 v57, v57, v57
	v_max_f32_e32 v59, v59, v59
	v_max_f32_e32 v60, v60, v60
	v_max_f32_e32 v56, v56, v56
	v_max_f32_e32 v61, v61, v61
	v_max_f32_e32 v62, v62, v62
	v_max_f32_e32 v58, v58, v58
	v_max_f32_e32 v63, v63, v63
	v_max_f32_e32 v41, v41, v41
	s_waitcnt vmcnt(0)
	v_mov_b32_e32 v160, v157
	v_mov_b32_e32 v161, v158
	v_mov_b32_e32 v157, v159
	v_pk_add_f32 v[156:157], v[160:161], v[156:157]
	v_lshlrev_b64 v[160:161], 6, v[162:163]
	v_add_f32_e32 v147, v156, v157
	ds_swizzle_b32 v155, v147 offset:swizzle(SWAP,16)
	v_lshl_add_u64 v[156:157], s[48:49], 0, v[164:165]
	v_lshl_add_u64 v[156:157], v[156:157], 0, v[112:113]
	v_lshl_add_u64 v[160:161], v[136:137], 0, v[160:161]
	v_max_f32_e32 v43, v43, v43
	s_waitcnt lgkmcnt(0)
	v_add_f32_e32 v147, v147, v155
	v_mov_b32_e32 v155, v147
	s_nop 1
	v_permlane32_swap_b32_e32 v147, v155
	v_add_f32_e32 v147, v147, v155
	v_fmamk_f32 v147, v147, 0x3a800000, v154
	v_rcp_f32_e32 v158, v147
	v_max_f32_e32 v44, v44, v44
	v_max_f32_e32 v40, v40, v40
	v_max_f32_e32 v45, v45, v45
	v_pk_mul_f32 v[116:117], v[116:117], v[158:159] op_sel_hi:[1,0]
	v_pk_mul_f32 v[164:165], v[166:167], v[158:159] op_sel_hi:[1,0]
	v_pk_mul_f32 v[166:167], v[114:115], v[158:159] op_sel_hi:[1,0]
	v_pk_mul_f32 v[118:119], v[118:119], v[158:159] op_sel_hi:[1,0]
	v_cvt_pk_bf16_f32 v114, v164, v165
	v_cvt_pk_bf16_f32 v115, v116, v117
	v_cvt_pk_bf16_f32 v116, v166, v167
	v_pk_mul_f32 v[120:121], v[120:121], v[158:159] op_sel_hi:[1,0]
	v_cvt_pk_bf16_f32 v117, v118, v119
	v_pk_mul_f32 v[124:125], v[124:125], v[158:159] op_sel_hi:[1,0]
	v_pk_mul_f32 v[122:123], v[122:123], v[158:159] op_sel_hi:[1,0]
	v_pk_mul_f32 v[126:127], v[126:127], v[158:159] op_sel_hi:[1,0]
	ds_bpermute_b32 v212, v200, v156
	ds_bpermute_b32 v213, v200, v157
	ds_bpermute_b32 v204, v200, v114
	ds_bpermute_b32 v205, v200, v115
	ds_bpermute_b32 v206, v200, v116
	ds_bpermute_b32 v207, v200, v117
	s_waitcnt lgkmcnt(0)
	global_store_dwordx4 v[212:213], v[204:207], off nt
	v_max_f32_e32 v118, v100, v100
	v_max_f32_e32 v119, v96, v96
	v_cvt_pk_bf16_f32 v114, v120, v121
	v_cvt_pk_bf16_f32 v115, v124, v125
	v_cvt_pk_bf16_f32 v116, v122, v123
	v_cvt_pk_bf16_f32 v117, v126, v127
	ds_bpermute_b32 v208, v200, v114
	ds_bpermute_b32 v209, v200, v115
	ds_bpermute_b32 v210, v200, v116
	ds_bpermute_b32 v211, v200, v117
	s_waitcnt lgkmcnt(0)
; template <int K> __device__ __forceinline__ float xor_swz(float v) { return __int_as_float(__builtin_amdgcn_ds_swizzle(__float_as_int(v), (K << 10) | 0x1f)); }
; __device__ __forceinline__ float half_sum(float v) { auto rr = __builtin_amdgcn_permlane32_swap(__float_as_uint(v), __float_as_uint(v), false, false); return __uint_as_float(rr[0]) + __uint_as_float(rr[1]); }
; __device__ __forceinline__ unsigned cvt_pk_bf16(float lo, float hi) { unsigned r; asm volatile("v_cvt_pk_bf16_f32 %0, %1, %2" : "=v"(r) : "v"(lo), "v"(hi)); return r; }
;     __device__ __forceinline__ void operator()(const f32x4 (&acc)[2][2][4][2], const Unit& u, int wr, int wc, int fr, int fq) const {
;     ...
;             for (int m = 0; m < 4; ++m) {
;                 const size_t row = (size_t)(row0 + ai * HALF + m * 16);
;                 const f32x4 pq = *(const f32x4*)(ssq + row * 16 + 4 * fq);
;                 float s = (pq[0] + pq[1]) + (pq[2] + pq[3]); s += xor_swz<16>(s); s = half_sum(s);
;                 const float r2 = __builtin_amdgcn_rcpf(s * (1.0f / 1024.0f) + 1e-6f);
;                 const f32x2v r2v = {r2, r2};
; #pragma unroll
;                 for (int bj = 0; bj < 2; ++bj) {
;                     f32x4 v0 = acc[ai][bj][m][0], v1 = acc[ai][bj][m][1];
; #pragma unroll
;                     for (int e = 0; e < 4; ++e) { v0[e] = fmaxf(v0[e], 0.f); v1[e] = fmaxf(v1[e], 0.f); }
;                     f32x2v a = {v0[0], v0[1]}, b = {v0[2], v0[3]}, c = {v1[0], v1[1]}, d = {v1[2], v1[3]};
;                     a = (a * a) * r2v; b = (b * b) * r2v; c = (c * c) * r2v; d = (d * d) * r2v;
;                     u32x4 w; w.x = cvt_pk_bf16(a.x, a.y); w.y = cvt_pk_bf16(b.x, b.y); w.z = cvt_pk_bf16(c.x, c.y); w.w = cvt_pk_bf16(d.x, d.y);
;                     __builtin_nontemporal_store(w, (u32x4*)(Z + row * 4096 + col0 + bj * HALF));
	global_store_dwordx4 v[212:213], v[208:211], off offset:256 nt
	global_load_dwordx4 v[114:117], v[160:161], off
	v_max_f32_e32 v120, v101, v101
	v_max_f32_e32 v121, v97, v97
	v_max_f32_e32 v124, v103, v103
	v_max_f32_e32 v125, v99, v99
	v_max_f32_e32 v99, 0, v105
	v_max_f32_e32 v103, 0, v107
	v_max_f32_e32 v105, 0, v120
	v_max_f32_e32 v107, 0, v121
	v_max_f32_e32 v123, v98, v98
	v_max_f32_e32 v96, 0, v108
	v_max_f32_e32 v98, 0, v104
	v_max_f32_e32 v97, 0, v109
	v_max_f32_e32 v122, v102, v102
	v_max_f32_e32 v100, 0, v110
	v_max_f32_e32 v102, 0, v106
	v_max_f32_e32 v101, 0, v111
	v_max_f32_e32 v104, 0, v118
	v_or_b32_e32 v118, 32, v146
	v_pk_mul_f32 v[96:97], v[96:97], v[96:97]
	v_pk_mul_f32 v[98:99], v[98:99], v[98:99]
	v_max_f32_e32 v106, 0, v119
	v_max_f32_e32 v108, 0, v122
	v_max_f32_e32 v110, 0, v123
	v_max_f32_e32 v109, 0, v124
	v_max_f32_e32 v111, 0, v125
	v_pk_mul_f32 v[100:101], v[100:101], v[100:101]
	v_pk_mul_f32 v[102:103], v[102:103], v[102:103]
	v_ashrrev_i32_e32 v119, 31, v118
	v_pk_mul_f32 v[108:109], v[108:109], v[108:109]
	v_pk_mul_f32 v[104:105], v[104:105], v[104:105]
	v_pk_mul_f32 v[110:111], v[110:111], v[110:111]
	v_pk_mul_f32 v[106:107], v[106:107], v[106:107]
	v_max_f32_e32 v46, v46, v46
	v_max_f32_e32 v42, v42, v42
	v_max_f32_e32 v47, v47, v47
	v_max_f32_e32 v25, v25, v25
	v_max_f32_e32 v27, v27, v27
	v_max_f32_e32 v28, v28, v28
	v_max_f32_e32 v24, v24, v24
	v_max_f32_e32 v29, v29, v29
	v_max_f32_e32 v30, v30, v30
	v_max_f32_e32 v26, v26, v26
	v_max_f32_e32 v31, v31, v31
	v_max_f32_e32 v8, v8, v8
	v_max_f32_e32 v10, v10, v10
	v_max_f32_e32 v12, v12, v12
	v_max_f32_e32 v13, v13, v13
	v_max_f32_e32 v9, v9, v9
	v_max_f32_e32 v14, v14, v14
	v_max_f32_e32 v15, v15, v15
	v_max_f32_e32 v11, v11, v11
	s_andn2_b64 vcc, exec, s[4:5]
	s_mov_b64 s[4:5], -1
	s_waitcnt vmcnt(0)
	v_mov_b32_e32 v120, v115
	v_mov_b32_e32 v121, v116
	v_mov_b32_e32 v115, v117
	v_pk_add_f32 v[114:115], v[120:121], v[114:115]
	v_lshlrev_b64 v[116:117], 6, v[118:119]
	v_add_f32_e32 v120, v114, v115
	ds_swizzle_b32 v121, v120 offset:swizzle(SWAP,16)
	v_lshlrev_b64 v[114:115], 13, v[162:163]
	v_lshl_add_u64 v[114:115], s[48:49], 0, v[114:115]
	v_lshl_add_u64 v[114:115], v[114:115], 0, v[112:113]
	v_lshl_add_u64 v[116:117], v[136:137], 0, v[116:117]
	s_waitcnt lgkmcnt(0)
	v_add_f32_e32 v120, v120, v121
	v_mov_b32_e32 v121, v120
	s_nop 1
	v_permlane32_swap_b32_e32 v120, v121
	v_add_f32_e32 v120, v120, v121
	v_fmamk_f32 v120, v120, 0x3a800000, v154
	v_rcp_f32_e32 v120, v120
	s_nop 0
	v_pk_mul_f32 v[96:97], v[96:97], v[120:121] op_sel_hi:[1,0]
	v_pk_mul_f32 v[98:99], v[98:99], v[120:121] op_sel_hi:[1,0]
	v_pk_mul_f32 v[100:101], v[100:101], v[120:121] op_sel_hi:[1,0]
	v_pk_mul_f32 v[102:103], v[102:103], v[120:121] op_sel_hi:[1,0]
	v_cvt_pk_bf16_f32 v96, v96, v97
	v_cvt_pk_bf16_f32 v97, v100, v101
	v_cvt_pk_bf16_f32 v98, v98, v99
	v_pk_mul_f32 v[104:105], v[104:105], v[120:121] op_sel_hi:[1,0]
	v_cvt_pk_bf16_f32 v99, v102, v103
	v_pk_mul_f32 v[108:109], v[108:109], v[120:121] op_sel_hi:[1,0]
	v_pk_mul_f32 v[106:107], v[106:107], v[120:121] op_sel_hi:[1,0]
	v_pk_mul_f32 v[110:111], v[110:111], v[120:121] op_sel_hi:[1,0]
	ds_bpermute_b32 v212, v200, v114
	ds_bpermute_b32 v213, v200, v115
	ds_bpermute_b32 v204, v200, v96
	ds_bpermute_b32 v205, v200, v97
	ds_bpermute_b32 v206, v200, v98
	ds_bpermute_b32 v207, v200, v99
	s_waitcnt lgkmcnt(0)
	global_store_dwordx4 v[212:213], v[204:207], off nt
	v_max_f32_e32 v102, v85, v85
	v_max_f32_e32 v103, v81, v81
	v_cvt_pk_bf16_f32 v96, v104, v105
	v_cvt_pk_bf16_f32 v97, v108, v109
	v_cvt_pk_bf16_f32 v98, v106, v107
	v_cvt_pk_bf16_f32 v99, v110, v111
	ds_bpermute_b32 v208, v200, v96
	ds_bpermute_b32 v209, v200, v97
	ds_bpermute_b32 v210, v200, v98
	ds_bpermute_b32 v211, v200, v99
	s_waitcnt lgkmcnt(0)
	global_store_dwordx4 v[212:213], v[208:211], off offset:256 nt
	global_load_dwordx4 v[96:99], v[116:117], off
	v_max_f32_e32 v106, v87, v87
	v_max_f32_e32 v107, v83, v83
	v_max_f32_e32 v83, 0, v89
	v_max_f32_e32 v87, 0, v91
	v_max_f32_e32 v89, 0, v102
	v_max_f32_e32 v91, 0, v103
	v_max_f32_e32 v100, v84, v84
	v_max_f32_e32 v101, v80, v80
	v_max_f32_e32 v105, v82, v82
	v_max_f32_e32 v80, 0, v92
	v_max_f32_e32 v82, 0, v88
	v_max_f32_e32 v81, 0, v93
	v_max_f32_e32 v104, v86, v86
	v_max_f32_e32 v84, 0, v94
	v_max_f32_e32 v86, 0, v90
	v_max_f32_e32 v85, 0, v95
	v_max_f32_e32 v88, 0, v100
	v_or_b32_e32 v100, 48, v146
	v_pk_mul_f32 v[80:81], v[80:81], v[80:81]
	v_pk_mul_f32 v[82:83], v[82:83], v[82:83]
	v_max_f32_e32 v90, 0, v101
	v_max_f32_e32 v92, 0, v104
	v_max_f32_e32 v94, 0, v105
	v_max_f32_e32 v93, 0, v106
	v_max_f32_e32 v95, 0, v107
	v_pk_mul_f32 v[84:85], v[84:85], v[84:85]
	v_pk_mul_f32 v[86:87], v[86:87], v[86:87]
	v_ashrrev_i32_e32 v101, 31, v100
	v_pk_mul_f32 v[92:93], v[92:93], v[92:93]
	v_pk_mul_f32 v[88:89], v[88:89], v[88:89]
	v_pk_mul_f32 v[94:95], v[94:95], v[94:95]
	v_pk_mul_f32 v[90:91], v[90:91], v[90:91]
	s_waitcnt vmcnt(0)
	v_mov_b32_e32 v102, v97
	v_mov_b32_e32 v103, v98
	v_mov_b32_e32 v97, v99
	v_pk_add_f32 v[96:97], v[102:103], v[96:97]
	v_lshlrev_b64 v[98:99], 6, v[100:101]
	v_add_f32_e32 v102, v96, v97
	ds_swizzle_b32 v103, v102 offset:swizzle(SWAP,16)
	v_lshlrev_b64 v[96:97], 13, v[118:119]
	v_lshl_add_u64 v[96:97], s[48:49], 0, v[96:97]
	v_lshl_add_u64 v[96:97], v[96:97], 0, v[112:113]
	v_lshl_add_u64 v[98:99], v[136:137], 0, v[98:99]
	s_waitcnt lgkmcnt(0)
; template <int K> __device__ __forceinline__ float xor_swz(float v) { return __int_as_float(__builtin_amdgcn_ds_swizzle(__float_as_int(v), (K << 10) | 0x1f)); }
; __device__ __forceinline__ float half_sum(float v) { auto rr = __builtin_amdgcn_permlane32_swap(__float_as_uint(v), __float_as_uint(v), false, false); return __uint_as_float(rr[0]) + __uint_as_float(rr[1]); }
; __device__ __forceinline__ unsigned cvt_pk_bf16(float lo, float hi) { unsigned r; asm volatile("v_cvt_pk_bf16_f32 %0, %1, %2" : "=v"(r) : "v"(lo), "v"(hi)); return r; }
;     __device__ __forceinline__ void operator()(const f32x4 (&acc)[2][2][4][2], const Unit& u, int wr, int wc, int fr, int fq) const {
;     ...
;             for (int m = 0; m < 4; ++m) {
;                 const size_t row = (size_t)(row0 + ai * HALF + m * 16);
;                 const f32x4 pq = *(const f32x4*)(ssq + row * 16 + 4 * fq);
;                 float s = (pq[0] + pq[1]) + (pq[2] + pq[3]); s += xor_swz<16>(s); s = half_sum(s);
;                 const float r2 = __builtin_amdgcn_rcpf(s * (1.0f / 1024.0f) + 1e-6f);
;                 const f32x2v r2v = {r2, r2};
; #pragma unroll
;                 for (int bj = 0; bj < 2; ++bj) {
;                     f32x4 v0 = acc[ai][bj][m][0], v1 = acc[ai][bj][m][1];
; #pragma unroll
;                     for (int e = 0; e < 4; ++e) { v0[e] = fmaxf(v0[e], 0.f); v1[e] = fmaxf(v1[e], 0.f); }
;                     f32x2v a = {v0[0], v0[1]}, b = {v0[2], v0[3]}, c = {v1[0], v1[1]}, d = {v1[2], v1[3]};
;                     a = (a * a) * r2v; b = (b * b) * r2v; c = (c * c) * r2v; d = (d * d) * r2v;
;                     u32x4 w; w.x = cvt_pk_bf16(a.x, a.y); w.y = cvt_pk_bf16(b.x, b.y); w.z = cvt_pk_bf16(c.x, c.y); w.w = cvt_pk_bf16(d.x, d.y);
;                     __builtin_nontemporal_store(w, (u32x4*)(Z + row * 4096 + col0 + bj * HALF));
	v_add_f32_e32 v102, v102, v103
	v_mov_b32_e32 v103, v102
	s_nop 1
	v_permlane32_swap_b32_e32 v102, v103
	v_add_f32_e32 v102, v102, v103
	v_fmamk_f32 v102, v102, 0x3a800000, v154
	v_rcp_f32_e32 v102, v102
	s_nop 0
	v_pk_mul_f32 v[80:81], v[80:81], v[102:103] op_sel_hi:[1,0]
	v_pk_mul_f32 v[82:83], v[82:83], v[102:103] op_sel_hi:[1,0]
	v_pk_mul_f32 v[84:85], v[84:85], v[102:103] op_sel_hi:[1,0]
	v_pk_mul_f32 v[86:87], v[86:87], v[102:103] op_sel_hi:[1,0]
	v_cvt_pk_bf16_f32 v80, v80, v81
	v_cvt_pk_bf16_f32 v81, v84, v85
	v_cvt_pk_bf16_f32 v82, v82, v83
	v_pk_mul_f32 v[88:89], v[88:89], v[102:103] op_sel_hi:[1,0]
	v_cvt_pk_bf16_f32 v83, v86, v87
	v_pk_mul_f32 v[92:93], v[92:93], v[102:103] op_sel_hi:[1,0]
	v_pk_mul_f32 v[90:91], v[90:91], v[102:103] op_sel_hi:[1,0]
	v_pk_mul_f32 v[94:95], v[94:95], v[102:103] op_sel_hi:[1,0]
	ds_bpermute_b32 v212, v200, v96
	ds_bpermute_b32 v213, v200, v97
	ds_bpermute_b32 v204, v200, v80
	ds_bpermute_b32 v205, v200, v81
	ds_bpermute_b32 v206, v200, v82
	ds_bpermute_b32 v207, v200, v83
	s_waitcnt lgkmcnt(0)
	global_store_dwordx4 v[212:213], v[204:207], off nt
	v_max_f32_e32 v86, v69, v69
	v_max_f32_e32 v87, v65, v65
	v_cvt_pk_bf16_f32 v80, v88, v89
	v_cvt_pk_bf16_f32 v81, v92, v93
	v_cvt_pk_bf16_f32 v82, v90, v91
	v_cvt_pk_bf16_f32 v83, v94, v95
	ds_bpermute_b32 v208, v200, v80
	ds_bpermute_b32 v209, v200, v81
	ds_bpermute_b32 v210, v200, v82
	ds_bpermute_b32 v211, v200, v83
	s_waitcnt lgkmcnt(0)
	global_store_dwordx4 v[212:213], v[208:211], off offset:256 nt
	global_load_dwordx4 v[80:83], v[98:99], off
	v_max_f32_e32 v90, v71, v71
	v_max_f32_e32 v91, v67, v67
	v_max_f32_e32 v67, 0, v73
	v_max_f32_e32 v71, 0, v75
	v_max_f32_e32 v73, 0, v86
	v_max_f32_e32 v75, 0, v87
	v_max_f32_e32 v84, v68, v68
	v_max_f32_e32 v85, v64, v64
	v_max_f32_e32 v89, v66, v66
	v_max_f32_e32 v64, 0, v76
	v_max_f32_e32 v66, 0, v72
	v_max_f32_e32 v65, 0, v77
	v_max_f32_e32 v88, v70, v70
	v_max_f32_e32 v68, 0, v78
	v_max_f32_e32 v70, 0, v74
	v_max_f32_e32 v69, 0, v79
	v_max_f32_e32 v72, 0, v84
	v_add_u32_e32 v84, 0x80, v146
	v_pk_mul_f32 v[64:65], v[64:65], v[64:65]
	v_pk_mul_f32 v[66:67], v[66:67], v[66:67]
	v_max_f32_e32 v74, 0, v85
	v_max_f32_e32 v76, 0, v88
	v_max_f32_e32 v78, 0, v89
	v_max_f32_e32 v77, 0, v90
	v_max_f32_e32 v79, 0, v91
	v_pk_mul_f32 v[68:69], v[68:69], v[68:69]
	v_pk_mul_f32 v[70:71], v[70:71], v[70:71]
	v_ashrrev_i32_e32 v85, 31, v84
	v_pk_mul_f32 v[76:77], v[76:77], v[76:77]
	v_pk_mul_f32 v[72:73], v[72:73], v[72:73]
	v_pk_mul_f32 v[78:79], v[78:79], v[78:79]
	v_pk_mul_f32 v[74:75], v[74:75], v[74:75]
	s_waitcnt vmcnt(0)
	v_mov_b32_e32 v86, v81
	v_mov_b32_e32 v87, v82
	v_mov_b32_e32 v81, v83
	v_pk_add_f32 v[80:81], v[86:87], v[80:81]
	v_lshlrev_b64 v[82:83], 6, v[84:85]
	v_add_f32_e32 v86, v80, v81
	ds_swizzle_b32 v87, v86 offset:swizzle(SWAP,16)
	v_lshlrev_b64 v[80:81], 13, v[100:101]
	v_lshl_add_u64 v[80:81], s[48:49], 0, v[80:81]
	v_lshl_add_u64 v[80:81], v[80:81], 0, v[112:113]
	v_lshl_add_u64 v[82:83], v[136:137], 0, v[82:83]
	s_waitcnt lgkmcnt(0)
	v_add_f32_e32 v86, v86, v87
	v_mov_b32_e32 v87, v86
	s_nop 1
	v_permlane32_swap_b32_e32 v86, v87
	v_add_f32_e32 v86, v86, v87
	v_fmamk_f32 v86, v86, 0x3a800000, v154
	v_rcp_f32_e32 v86, v86
	s_nop 0
	v_pk_mul_f32 v[64:65], v[64:65], v[86:87] op_sel_hi:[1,0]
	v_pk_mul_f32 v[66:67], v[66:67], v[86:87] op_sel_hi:[1,0]
	v_pk_mul_f32 v[68:69], v[68:69], v[86:87] op_sel_hi:[1,0]
	v_pk_mul_f32 v[70:71], v[70:71], v[86:87] op_sel_hi:[1,0]
	v_cvt_pk_bf16_f32 v64, v64, v65
	v_cvt_pk_bf16_f32 v65, v68, v69
	v_cvt_pk_bf16_f32 v66, v66, v67
	v_pk_mul_f32 v[72:73], v[72:73], v[86:87] op_sel_hi:[1,0]
	v_cvt_pk_bf16_f32 v67, v70, v71
	v_pk_mul_f32 v[76:77], v[76:77], v[86:87] op_sel_hi:[1,0]
	v_pk_mul_f32 v[74:75], v[74:75], v[86:87] op_sel_hi:[1,0]
	v_pk_mul_f32 v[78:79], v[78:79], v[86:87] op_sel_hi:[1,0]
	ds_bpermute_b32 v212, v200, v80
	ds_bpermute_b32 v213, v200, v81
	ds_bpermute_b32 v204, v200, v64
	ds_bpermute_b32 v205, v200, v65
	ds_bpermute_b32 v206, v200, v66
	ds_bpermute_b32 v207, v200, v67
	s_waitcnt lgkmcnt(0)
	global_store_dwordx4 v[212:213], v[204:207], off nt
	v_max_f32_e32 v70, v53, v53
	v_max_f32_e32 v71, v49, v49
	v_cvt_pk_bf16_f32 v64, v72, v73
	v_cvt_pk_bf16_f32 v65, v76, v77
	v_cvt_pk_bf16_f32 v66, v74, v75
	v_cvt_pk_bf16_f32 v67, v78, v79
	ds_bpermute_b32 v208, v200, v64
	ds_bpermute_b32 v209, v200, v65
	ds_bpermute_b32 v210, v200, v66
	ds_bpermute_b32 v211, v200, v67
	s_waitcnt lgkmcnt(0)
	global_store_dwordx4 v[212:213], v[208:211], off offset:256 nt
	global_load_dwordx4 v[64:67], v[82:83], off
	v_max_f32_e32 v74, v55, v55
	v_max_f32_e32 v75, v51, v51
	v_max_f32_e32 v51, 0, v57
	v_max_f32_e32 v55, 0, v59
	v_max_f32_e32 v57, 0, v70
	v_max_f32_e32 v59, 0, v71
	v_max_f32_e32 v68, v52, v52
	v_max_f32_e32 v69, v48, v48
	v_max_f32_e32 v73, v50, v50
	v_max_f32_e32 v48, 0, v60
	v_max_f32_e32 v50, 0, v56
	v_max_f32_e32 v49, 0, v61
	v_max_f32_e32 v72, v54, v54
	v_max_f32_e32 v52, 0, v62
	v_max_f32_e32 v54, 0, v58
	v_max_f32_e32 v53, 0, v63
	v_max_f32_e32 v56, 0, v68
	v_add_u32_e32 v68, 0x90, v146
	v_pk_mul_f32 v[48:49], v[48:49], v[48:49]
	v_pk_mul_f32 v[50:51], v[50:51], v[50:51]
	v_max_f32_e32 v58, 0, v69
	v_max_f32_e32 v60, 0, v72
	v_max_f32_e32 v62, 0, v73
	v_max_f32_e32 v61, 0, v74
	v_max_f32_e32 v63, 0, v75
	v_pk_mul_f32 v[52:53], v[52:53], v[52:53]
	v_pk_mul_f32 v[54:55], v[54:55], v[54:55]
	v_ashrrev_i32_e32 v69, 31, v68
	v_pk_mul_f32 v[60:61], v[60:61], v[60:61]
	v_pk_mul_f32 v[56:57], v[56:57], v[56:57]
	v_pk_mul_f32 v[62:63], v[62:63], v[62:63]
	v_pk_mul_f32 v[58:59], v[58:59], v[58:59]
	s_waitcnt vmcnt(0)
; template <int K> __device__ __forceinline__ float xor_swz(float v) { return __int_as_float(__builtin_amdgcn_ds_swizzle(__float_as_int(v), (K << 10) | 0x1f)); }
; __device__ __forceinline__ float half_sum(float v) { auto rr = __builtin_amdgcn_permlane32_swap(__float_as_uint(v), __float_as_uint(v), false, false); return __uint_as_float(rr[0]) + __uint_as_float(rr[1]); }
; __device__ __forceinline__ unsigned cvt_pk_bf16(float lo, float hi) { unsigned r; asm volatile("v_cvt_pk_bf16_f32 %0, %1, %2" : "=v"(r) : "v"(lo), "v"(hi)); return r; }
;     __device__ __forceinline__ void operator()(const f32x4 (&acc)[2][2][4][2], const Unit& u, int wr, int wc, int fr, int fq) const {
;     ...
;             for (int m = 0; m < 4; ++m) {
;                 const size_t row = (size_t)(row0 + ai * HALF + m * 16);
;                 const f32x4 pq = *(const f32x4*)(ssq + row * 16 + 4 * fq);
;                 float s = (pq[0] + pq[1]) + (pq[2] + pq[3]); s += xor_swz<16>(s); s = half_sum(s);
;                 const float r2 = __builtin_amdgcn_rcpf(s * (1.0f / 1024.0f) + 1e-6f);
;                 const f32x2v r2v = {r2, r2};
; #pragma unroll
;                 for (int bj = 0; bj < 2; ++bj) {
;                     f32x4 v0 = acc[ai][bj][m][0], v1 = acc[ai][bj][m][1];
; #pragma unroll
;                     for (int e = 0; e < 4; ++e) { v0[e] = fmaxf(v0[e], 0.f); v1[e] = fmaxf(v1[e], 0.f); }
;                     f32x2v a = {v0[0], v0[1]}, b = {v0[2], v0[3]}, c = {v1[0], v1[1]}, d = {v1[2], v1[3]};
;                     a = (a * a) * r2v; b = (b * b) * r2v; c = (c * c) * r2v; d = (d * d) * r2v;
;                     u32x4 w; w.x = cvt_pk_bf16(a.x, a.y); w.y = cvt_pk_bf16(b.x, b.y); w.z = cvt_pk_bf16(c.x, c.y); w.w = cvt_pk_bf16(d.x, d.y);
;                     __builtin_nontemporal_store(w, (u32x4*)(Z + row * 4096 + col0 + bj * HALF));
	v_mov_b32_e32 v70, v65
	v_mov_b32_e32 v71, v66
	v_mov_b32_e32 v65, v67
	v_pk_add_f32 v[64:65], v[70:71], v[64:65]
	v_lshlrev_b64 v[66:67], 6, v[68:69]
	v_add_f32_e32 v70, v64, v65
	ds_swizzle_b32 v71, v70 offset:swizzle(SWAP,16)
	v_lshlrev_b64 v[64:65], 13, v[84:85]
	v_lshl_add_u64 v[64:65], s[48:49], 0, v[64:65]
	v_lshl_add_u64 v[64:65], v[64:65], 0, v[112:113]
	v_lshl_add_u64 v[66:67], v[136:137], 0, v[66:67]
	s_waitcnt lgkmcnt(0)
	v_add_f32_e32 v70, v70, v71
	v_mov_b32_e32 v71, v70
	s_nop 1
	v_permlane32_swap_b32_e32 v70, v71
	v_add_f32_e32 v70, v70, v71
	v_fmamk_f32 v70, v70, 0x3a800000, v154
	v_rcp_f32_e32 v70, v70
	s_nop 0
	v_pk_mul_f32 v[48:49], v[48:49], v[70:71] op_sel_hi:[1,0]
	v_pk_mul_f32 v[50:51], v[50:51], v[70:71] op_sel_hi:[1,0]
	v_pk_mul_f32 v[52:53], v[52:53], v[70:71] op_sel_hi:[1,0]
	v_pk_mul_f32 v[54:55], v[54:55], v[70:71] op_sel_hi:[1,0]
	v_cvt_pk_bf16_f32 v48, v48, v49
	v_cvt_pk_bf16_f32 v49, v52, v53
	v_cvt_pk_bf16_f32 v50, v50, v51
	v_pk_mul_f32 v[56:57], v[56:57], v[70:71] op_sel_hi:[1,0]
	v_cvt_pk_bf16_f32 v51, v54, v55
	v_pk_mul_f32 v[60:61], v[60:61], v[70:71] op_sel_hi:[1,0]
	v_pk_mul_f32 v[58:59], v[58:59], v[70:71] op_sel_hi:[1,0]
	v_pk_mul_f32 v[62:63], v[62:63], v[70:71] op_sel_hi:[1,0]
	ds_bpermute_b32 v212, v200, v64
	ds_bpermute_b32 v213, v200, v65
	ds_bpermute_b32 v204, v200, v48
	ds_bpermute_b32 v205, v200, v49
	ds_bpermute_b32 v206, v200, v50
	ds_bpermute_b32 v207, v200, v51
	s_waitcnt lgkmcnt(0)
	global_store_dwordx4 v[212:213], v[204:207], off nt
	v_max_f32_e32 v54, v37, v37
	v_max_f32_e32 v55, v33, v33
	v_cvt_pk_bf16_f32 v48, v56, v57
	v_cvt_pk_bf16_f32 v49, v60, v61
	v_cvt_pk_bf16_f32 v50, v58, v59
	v_cvt_pk_bf16_f32 v51, v62, v63
	ds_bpermute_b32 v208, v200, v48
	ds_bpermute_b32 v209, v200, v49
	ds_bpermute_b32 v210, v200, v50
	ds_bpermute_b32 v211, v200, v51
	s_waitcnt lgkmcnt(0)
	global_store_dwordx4 v[212:213], v[208:211], off offset:256 nt
	global_load_dwordx4 v[48:51], v[66:67], off
	v_max_f32_e32 v58, v39, v39
	v_max_f32_e32 v59, v35, v35
	v_max_f32_e32 v35, 0, v41
	v_max_f32_e32 v39, 0, v43
	v_max_f32_e32 v41, 0, v54
	v_max_f32_e32 v43, 0, v55
	v_max_f32_e32 v52, v36, v36
	v_max_f32_e32 v53, v32, v32
	v_max_f32_e32 v57, v34, v34
	v_max_f32_e32 v32, 0, v44
	v_max_f32_e32 v34, 0, v40
	v_max_f32_e32 v33, 0, v45
	v_max_f32_e32 v56, v38, v38
	v_max_f32_e32 v36, 0, v46
	v_max_f32_e32 v38, 0, v42
	v_max_f32_e32 v37, 0, v47
	v_max_f32_e32 v40, 0, v52
	v_add_u32_e32 v52, 0xa0, v146
	v_pk_mul_f32 v[32:33], v[32:33], v[32:33]
	v_pk_mul_f32 v[34:35], v[34:35], v[34:35]
	v_max_f32_e32 v42, 0, v53
	v_max_f32_e32 v44, 0, v56
	v_max_f32_e32 v46, 0, v57
	v_max_f32_e32 v45, 0, v58
	v_max_f32_e32 v47, 0, v59
	v_pk_mul_f32 v[36:37], v[36:37], v[36:37]
	v_pk_mul_f32 v[38:39], v[38:39], v[38:39]
	v_ashrrev_i32_e32 v53, 31, v52
	v_pk_mul_f32 v[44:45], v[44:45], v[44:45]
	v_pk_mul_f32 v[40:41], v[40:41], v[40:41]
	v_pk_mul_f32 v[46:47], v[46:47], v[46:47]
	v_pk_mul_f32 v[42:43], v[42:43], v[42:43]
	s_waitcnt vmcnt(0)
	v_mov_b32_e32 v54, v49
	v_mov_b32_e32 v55, v50
	v_mov_b32_e32 v49, v51
	v_pk_add_f32 v[48:49], v[54:55], v[48:49]
	v_lshlrev_b64 v[50:51], 6, v[52:53]
	v_add_f32_e32 v54, v48, v49
	ds_swizzle_b32 v55, v54 offset:swizzle(SWAP,16)
	v_lshlrev_b64 v[48:49], 13, v[68:69]
	v_lshl_add_u64 v[48:49], s[48:49], 0, v[48:49]
	v_lshl_add_u64 v[48:49], v[48:49], 0, v[112:113]
	v_lshl_add_u64 v[50:51], v[136:137], 0, v[50:51]
	s_waitcnt lgkmcnt(0)
	v_add_f32_e32 v54, v54, v55
	v_mov_b32_e32 v55, v54
	s_nop 1
	v_permlane32_swap_b32_e32 v54, v55
	v_add_f32_e32 v54, v54, v55
	v_fmamk_f32 v54, v54, 0x3a800000, v154
	v_rcp_f32_e32 v54, v54
	s_nop 0
	v_pk_mul_f32 v[32:33], v[32:33], v[54:55] op_sel_hi:[1,0]
	v_pk_mul_f32 v[34:35], v[34:35], v[54:55] op_sel_hi:[1,0]
	v_pk_mul_f32 v[36:37], v[36:37], v[54:55] op_sel_hi:[1,0]
	v_pk_mul_f32 v[38:39], v[38:39], v[54:55] op_sel_hi:[1,0]
	v_cvt_pk_bf16_f32 v32, v32, v33
	v_cvt_pk_bf16_f32 v33, v36, v37
	v_cvt_pk_bf16_f32 v34, v34, v35
	v_pk_mul_f32 v[40:41], v[40:41], v[54:55] op_sel_hi:[1,0]
	v_cvt_pk_bf16_f32 v35, v38, v39
	v_pk_mul_f32 v[44:45], v[44:45], v[54:55] op_sel_hi:[1,0]
	v_pk_mul_f32 v[42:43], v[42:43], v[54:55] op_sel_hi:[1,0]
	v_pk_mul_f32 v[46:47], v[46:47], v[54:55] op_sel_hi:[1,0]
	ds_bpermute_b32 v212, v200, v48
	ds_bpermute_b32 v213, v200, v49
	ds_bpermute_b32 v204, v200, v32
	ds_bpermute_b32 v205, v200, v33
	ds_bpermute_b32 v206, v200, v34
	ds_bpermute_b32 v207, v200, v35
	s_waitcnt lgkmcnt(0)
	global_store_dwordx4 v[212:213], v[204:207], off nt
	v_max_f32_e32 v38, v21, v21
	v_max_f32_e32 v39, v17, v17
	v_cvt_pk_bf16_f32 v32, v40, v41
	v_cvt_pk_bf16_f32 v33, v44, v45
	v_cvt_pk_bf16_f32 v34, v42, v43
	v_cvt_pk_bf16_f32 v35, v46, v47
	ds_bpermute_b32 v208, v200, v32
	ds_bpermute_b32 v209, v200, v33
	ds_bpermute_b32 v210, v200, v34
	ds_bpermute_b32 v211, v200, v35
	s_waitcnt lgkmcnt(0)
; template <int K> __device__ __forceinline__ float xor_swz(float v) { return __int_as_float(__builtin_amdgcn_ds_swizzle(__float_as_int(v), (K << 10) | 0x1f)); }
; __device__ __forceinline__ float half_sum(float v) { auto rr = __builtin_amdgcn_permlane32_swap(__float_as_uint(v), __float_as_uint(v), false, false); return __uint_as_float(rr[0]) + __uint_as_float(rr[1]); }
; __device__ __forceinline__ unsigned cvt_pk_bf16(float lo, float hi) { unsigned r; asm volatile("v_cvt_pk_bf16_f32 %0, %1, %2" : "=v"(r) : "v"(lo), "v"(hi)); return r; }
;     __device__ __forceinline__ void operator()(const f32x4 (&acc)[2][2][4][2], const Unit& u, int wr, int wc, int fr, int fq) const {
;     ...
;             for (int m = 0; m < 4; ++m) {
;                 const size_t row = (size_t)(row0 + ai * HALF + m * 16);
;                 const f32x4 pq = *(const f32x4*)(ssq + row * 16 + 4 * fq);
;                 float s = (pq[0] + pq[1]) + (pq[2] + pq[3]); s += xor_swz<16>(s); s = half_sum(s);
;                 const float r2 = __builtin_amdgcn_rcpf(s * (1.0f / 1024.0f) + 1e-6f);
;                 const f32x2v r2v = {r2, r2};
; #pragma unroll
;                 for (int bj = 0; bj < 2; ++bj) {
;                     f32x4 v0 = acc[ai][bj][m][0], v1 = acc[ai][bj][m][1];
; #pragma unroll
;                     for (int e = 0; e < 4; ++e) { v0[e] = fmaxf(v0[e], 0.f); v1[e] = fmaxf(v1[e], 0.f); }
;                     f32x2v a = {v0[0], v0[1]}, b = {v0[2], v0[3]}, c = {v1[0], v1[1]}, d = {v1[2], v1[3]};
;                     a = (a * a) * r2v; b = (b * b) * r2v; c = (c * c) * r2v; d = (d * d) * r2v;
;                     u32x4 w; w.x = cvt_pk_bf16(a.x, a.y); w.y = cvt_pk_bf16(b.x, b.y); w.z = cvt_pk_bf16(c.x, c.y); w.w = cvt_pk_bf16(d.x, d.y);
;                     __builtin_nontemporal_store(w, (u32x4*)(Z + row * 4096 + col0 + bj * HALF));
;                 }
	global_store_dwordx4 v[212:213], v[208:211], off offset:256 nt
	global_load_dwordx4 v[32:35], v[50:51], off
	v_max_f32_e32 v42, v23, v23
	v_max_f32_e32 v43, v19, v19
	v_max_f32_e32 v19, 0, v25
	v_max_f32_e32 v23, 0, v27
	v_max_f32_e32 v25, 0, v38
	v_max_f32_e32 v27, 0, v39
	v_max_f32_e32 v36, v20, v20
	v_max_f32_e32 v37, v16, v16
	v_max_f32_e32 v41, v18, v18
	v_max_f32_e32 v16, 0, v28
	v_max_f32_e32 v18, 0, v24
	v_max_f32_e32 v17, 0, v29
	v_max_f32_e32 v40, v22, v22
	v_max_f32_e32 v20, 0, v30
	v_max_f32_e32 v22, 0, v26
	v_max_f32_e32 v21, 0, v31
	v_max_f32_e32 v24, 0, v36
	v_add_u32_e32 v36, 0xb0, v146
	v_pk_mul_f32 v[16:17], v[16:17], v[16:17]
	v_pk_mul_f32 v[18:19], v[18:19], v[18:19]
	v_max_f32_e32 v26, 0, v37
	v_max_f32_e32 v28, 0, v40
	v_max_f32_e32 v30, 0, v41
	v_max_f32_e32 v29, 0, v42
	v_max_f32_e32 v31, 0, v43
	v_pk_mul_f32 v[20:21], v[20:21], v[20:21]
	v_pk_mul_f32 v[22:23], v[22:23], v[22:23]
	v_ashrrev_i32_e32 v37, 31, v36
	v_pk_mul_f32 v[28:29], v[28:29], v[28:29]
	v_pk_mul_f32 v[24:25], v[24:25], v[24:25]
	v_pk_mul_f32 v[30:31], v[30:31], v[30:31]
	v_pk_mul_f32 v[26:27], v[26:27], v[26:27]
	s_waitcnt vmcnt(0)
	v_mov_b32_e32 v38, v33
	v_mov_b32_e32 v39, v34
	v_mov_b32_e32 v33, v35
	v_pk_add_f32 v[32:33], v[38:39], v[32:33]
	v_lshlrev_b64 v[34:35], 6, v[36:37]
	v_add_f32_e32 v38, v32, v33
	ds_swizzle_b32 v39, v38 offset:swizzle(SWAP,16)
	v_lshlrev_b64 v[32:33], 13, v[52:53]
	v_lshl_add_u64 v[32:33], s[48:49], 0, v[32:33]
	v_lshl_add_u64 v[32:33], v[32:33], 0, v[112:113]
	v_lshl_add_u64 v[34:35], v[136:137], 0, v[34:35]
	s_waitcnt lgkmcnt(0)
	v_add_f32_e32 v38, v38, v39
	v_mov_b32_e32 v39, v38
	s_nop 1
	v_permlane32_swap_b32_e32 v38, v39
	v_add_f32_e32 v38, v38, v39
	v_fmamk_f32 v38, v38, 0x3a800000, v154
	v_rcp_f32_e32 v38, v38
	s_nop 0
	v_pk_mul_f32 v[16:17], v[16:17], v[38:39] op_sel_hi:[1,0]
	v_pk_mul_f32 v[18:19], v[18:19], v[38:39] op_sel_hi:[1,0]
	v_pk_mul_f32 v[20:21], v[20:21], v[38:39] op_sel_hi:[1,0]
	v_pk_mul_f32 v[22:23], v[22:23], v[38:39] op_sel_hi:[1,0]
	v_cvt_pk_bf16_f32 v16, v16, v17
	v_cvt_pk_bf16_f32 v17, v20, v21
	v_cvt_pk_bf16_f32 v18, v18, v19
	v_pk_mul_f32 v[24:25], v[24:25], v[38:39] op_sel_hi:[1,0]
	v_cvt_pk_bf16_f32 v19, v22, v23
	v_pk_mul_f32 v[28:29], v[28:29], v[38:39] op_sel_hi:[1,0]
	v_pk_mul_f32 v[26:27], v[26:27], v[38:39] op_sel_hi:[1,0]
	v_pk_mul_f32 v[30:31], v[30:31], v[38:39] op_sel_hi:[1,0]
	ds_bpermute_b32 v212, v200, v32
	ds_bpermute_b32 v213, v200, v33
	ds_bpermute_b32 v204, v200, v16
	ds_bpermute_b32 v205, v200, v17
	ds_bpermute_b32 v206, v200, v18
	ds_bpermute_b32 v207, v200, v19
	s_waitcnt lgkmcnt(0)
	global_store_dwordx4 v[212:213], v[204:207], off nt
	v_max_f32_e32 v20, v4, v4
	v_max_f32_e32 v21, v0, v0
	v_cvt_pk_bf16_f32 v16, v24, v25
	v_cvt_pk_bf16_f32 v17, v28, v29
	v_cvt_pk_bf16_f32 v18, v26, v27
	v_cvt_pk_bf16_f32 v19, v30, v31
	ds_bpermute_b32 v208, v200, v16
	ds_bpermute_b32 v209, v200, v17
	ds_bpermute_b32 v210, v200, v18
	ds_bpermute_b32 v211, v200, v19
	s_waitcnt lgkmcnt(0)
	global_store_dwordx4 v[212:213], v[208:211], off offset:256 nt
	global_load_dwordx4 v[16:19], v[34:35], off
	v_max_f32_e32 v24, v6, v6
	v_max_f32_e32 v25, v2, v2
	v_max_f32_e32 v2, 0, v8
	v_max_f32_e32 v6, 0, v10
	v_max_f32_e32 v8, 0, v20
	v_max_f32_e32 v10, 0, v21
	v_max_f32_e32 v23, v1, v1
	v_max_f32_e32 v27, v3, v3
	v_max_f32_e32 v0, 0, v12
	v_max_f32_e32 v1, 0, v13
	v_max_f32_e32 v3, 0, v9
	v_max_f32_e32 v22, v5, v5
	v_max_f32_e32 v26, v7, v7
	v_max_f32_e32 v4, 0, v14
	v_max_f32_e32 v5, 0, v15
	v_max_f32_e32 v7, 0, v11
	v_pk_mul_f32 v[0:1], v[0:1], v[0:1]
	v_pk_mul_f32 v[2:3], v[2:3], v[2:3]
	v_max_f32_e32 v9, 0, v22
	v_max_f32_e32 v11, 0, v23
	v_max_f32_e32 v12, 0, v24
	v_max_f32_e32 v14, 0, v25
	v_max_f32_e32 v13, 0, v26
	v_max_f32_e32 v15, 0, v27
	v_pk_mul_f32 v[4:5], v[4:5], v[4:5]
	v_pk_mul_f32 v[6:7], v[6:7], v[6:7]
	v_pk_mul_f32 v[12:13], v[12:13], v[12:13]
	v_pk_mul_f32 v[8:9], v[8:9], v[8:9]
	v_pk_mul_f32 v[14:15], v[14:15], v[14:15]
	v_pk_mul_f32 v[10:11], v[10:11], v[10:11]
	s_waitcnt vmcnt(0)
	v_mov_b32_e32 v20, v17
	v_mov_b32_e32 v21, v18
	v_mov_b32_e32 v17, v19
	v_pk_add_f32 v[16:17], v[20:21], v[16:17]
	v_lshlrev_b64 v[18:19], 13, v[36:37]
	v_add_f32_e32 v16, v16, v17
	ds_swizzle_b32 v17, v16 offset:swizzle(SWAP,16)
	v_lshl_add_u64 v[18:19], s[48:49], 0, v[18:19]
	v_lshl_add_u64 v[18:19], v[18:19], 0, v[112:113]
	s_waitcnt lgkmcnt(0)
	v_add_f32_e32 v16, v16, v17
	v_mov_b32_e32 v17, v16
	s_nop 1
	v_permlane32_swap_b32_e32 v16, v17
	v_add_f32_e32 v16, v16, v17
	v_fmamk_f32 v16, v16, 0x3a800000, v154
	v_rcp_f32_e32 v16, v16
	s_nop 0
	v_pk_mul_f32 v[0:1], v[0:1], v[16:17] op_sel_hi:[1,0]
	v_pk_mul_f32 v[2:3], v[2:3], v[16:17] op_sel_hi:[1,0]
	v_pk_mul_f32 v[4:5], v[4:5], v[16:17] op_sel_hi:[1,0]
	v_pk_mul_f32 v[6:7], v[6:7], v[16:17] op_sel_hi:[1,0]
	v_cvt_pk_bf16_f32 v0, v0, v1
	v_cvt_pk_bf16_f32 v1, v4, v5
	v_cvt_pk_bf16_f32 v2, v2, v3
	v_pk_mul_f32 v[8:9], v[8:9], v[16:17] op_sel_hi:[1,0]
	v_cvt_pk_bf16_f32 v3, v6, v7
	v_pk_mul_f32 v[12:13], v[12:13], v[16:17] op_sel_hi:[1,0]
	v_pk_mul_f32 v[10:11], v[10:11], v[16:17] op_sel_hi:[1,0]
	v_pk_mul_f32 v[14:15], v[14:15], v[16:17] op_sel_hi:[1,0]
	ds_bpermute_b32 v212, v200, v18
	ds_bpermute_b32 v213, v200, v19
	ds_bpermute_b32 v204, v200, v0
	ds_bpermute_b32 v205, v200, v1
	ds_bpermute_b32 v206, v200, v2
	ds_bpermute_b32 v207, v200, v3
	s_waitcnt lgkmcnt(0)
	global_store_dwordx4 v[212:213], v[204:207], off nt
	s_nop 1
	v_cvt_pk_bf16_f32 v0, v8, v9
	v_cvt_pk_bf16_f32 v1, v12, v13
	v_cvt_pk_bf16_f32 v2, v10, v11
	v_cvt_pk_bf16_f32 v3, v14, v15
	ds_bpermute_b32 v208, v200, v0
	ds_bpermute_b32 v209, v200, v1
	ds_bpermute_b32 v210, v200, v2
	ds_bpermute_b32 v211, v200, v3
	s_waitcnt lgkmcnt(0)
	global_store_dwordx4 v[212:213], v[208:211], off offset:256 nt
	s_cbranch_vccnz .LBB0_454
	s_andn2_b64 vcc, exec, s[6:7]
	s_cbranch_vccnz .LBB0_453
	s_barrier
	s_branch .LBB0_453
